# conv tap loop rewritten: eight LDS reads of a tap issued together, next tap weights loaded one tap ahead
# speedup vs baseline: 1.0437x; 1.0055x over previous
.LBB0_360:
	s_or_b64 exec, exec, s[18:19]
	v_and_b32_e32 v0, 63, v33
	v_ashrrev_i32_e32 v9, 4, v33
	v_lshlrev_b32_e32 v168, 5, v0
	v_lshrrev_b32_e32 v1, 2, v9
	s_movk_i32 s4, 0x2040
	v_lshlrev_b32_e32 v8, 3, v0
	v_lshl_add_u64 v[10:11], s[44:45], 0, v[168:169]
	v_lshlrev_b32_e32 v0, 4, v0
	v_mul_lo_u32 v1, v1, s4
	v_mov_b32_e32 v16, 0
	v_add3_u32 v72, v1, v0, 0
	s_movk_i32 s4, 0x400
	v_mov_b64_e32 v[32:33], v[10:11]
	v_mov_b32_e32 v17, v16
	v_mov_b32_e32 v18, v16
	v_mov_b32_e32 v19, v16
	v_mov_b32_e32 v38, v16
	v_mov_b32_e32 v39, v16
	v_mov_b32_e32 v40, v16
	v_mov_b32_e32 v41, v16
	v_mov_b32_e32 v54, v16
	v_mov_b32_e32 v55, v16
	v_mov_b32_e32 v56, v16
	v_mov_b32_e32 v57, v16
	v_mov_b32_e32 v0, v16
	v_mov_b32_e32 v1, v16
	v_mov_b32_e32 v2, v16
	v_mov_b32_e32 v3, v16
	v_mov_b32_e32 v20, v16
	v_mov_b32_e32 v21, v16
	v_mov_b32_e32 v22, v16
	v_mov_b32_e32 v23, v16
	v_mov_b32_e32 v24, v16
	v_mov_b32_e32 v25, v16
	v_mov_b32_e32 v26, v16
	v_mov_b32_e32 v27, v16
	v_mov_b32_e32 v28, v16
	v_mov_b32_e32 v29, v16
	v_mov_b32_e32 v30, v16
	v_mov_b32_e32 v31, v16
	v_mov_b32_e32 v42, v16
	v_mov_b32_e32 v43, v16
	v_mov_b32_e32 v44, v16
	v_mov_b32_e32 v45, v16
	v_mov_b32_e32 v46, v16
	v_mov_b32_e32 v47, v16
	v_mov_b32_e32 v48, v16
	v_mov_b32_e32 v49, v16
	v_mov_b32_e32 v50, v16
	v_mov_b32_e32 v51, v16
	v_mov_b32_e32 v52, v16
	v_mov_b32_e32 v53, v16
	v_mov_b32_e32 v58, v16
	v_mov_b32_e32 v59, v16
	v_mov_b32_e32 v60, v16
	v_mov_b32_e32 v61, v16
	v_mov_b32_e32 v62, v16
	v_mov_b32_e32 v63, v16
	v_mov_b32_e32 v64, v16
	v_mov_b32_e32 v65, v16
	v_mov_b32_e32 v66, v16
	v_mov_b32_e32 v67, v16
	v_mov_b32_e32 v68, v16
	v_mov_b32_e32 v69, v16
	v_mov_b32_e32 v4, v16
	v_mov_b32_e32 v5, v16
	v_mov_b32_e32 v6, v16
	v_mov_b32_e32 v7, v16
	v_mov_b32_e32 v12, v16
	v_mov_b32_e32 v13, v16
	v_mov_b32_e32 v14, v16
	v_mov_b32_e32 v15, v16
	v_mov_b32_e32 v34, v16
	v_mov_b32_e32 v35, v16
	v_mov_b32_e32 v36, v16
	v_mov_b32_e32 v37, v16
	s_waitcnt lgkmcnt(0)
	s_barrier
	global_load_dwordx4 v[128:131], v[32:33], off offset:16
	global_load_dwordx4 v[124:127], v[32:33], off
	global_load_dwordx4 v[136:139], v[32:33], off offset:2064
	global_load_dwordx4 v[132:135], v[32:33], off offset:2048
	s_waitcnt vmcnt(0)
.LBB0_361:
	ds_read_b128 v[156:159], v72
	ds_read_b128 v[160:163], v72 offset:2064
	ds_read_b128 v[164:167], v72 offset:4128
	ds_read_b128 v[178:181], v72 offset:6192
	ds_read_b128 v[182:185], v72 offset:1024
	ds_read_b128 v[186:189], v72 offset:3088
	ds_read_b128 v[190:193], v72 offset:5152
	ds_read_b128 v[194:197], v72 offset:7216
	s_cmpk_lg_i32 s4, 0x7c00
	s_cselect_b32 s70, s4, 0x7800
	v_lshl_add_u64 v[70:71], s[70:71], 2, v[10:11]
	v_add_u32_e32 v73, 0x810, v72
	s_addk_i32 s4, 0x400
	s_cmpk_lg_u32 s4, 0x8000
	global_load_dwordx4 v[144:147], v[70:71], off offset:16
	global_load_dwordx4 v[140:143], v[70:71], off
	global_load_dwordx4 v[152:155], v[70:71], off offset:2064
	global_load_dwordx4 v[148:151], v[70:71], off offset:2048
	s_waitcnt lgkmcnt(7)
	v_lshlrev_b32_e32 v86, 16, v156
	v_and_b32_e32 v87, 0xffff0000, v156
	v_lshlrev_b32_e32 v88, 16, v157
	v_and_b32_e32 v89, 0xffff0000, v157
	v_lshlrev_b32_e32 v90, 16, v158
	v_and_b32_e32 v91, 0xffff0000, v158
	v_lshlrev_b32_e32 v92, 16, v159
	v_and_b32_e32 v93, 0xffff0000, v159
	v_pk_fma_f32 v[36:37], v[124:125], v[86:87], v[36:37]
	v_pk_fma_f32 v[34:35], v[126:127], v[88:89], v[34:35]
	v_pk_fma_f32 v[14:15], v[128:129], v[90:91], v[14:15]
	v_pk_fma_f32 v[12:13], v[130:131], v[92:93], v[12:13]
	s_waitcnt lgkmcnt(6)
	v_lshlrev_b32_e32 v94, 16, v160
	v_and_b32_e32 v95, 0xffff0000, v160
	v_lshlrev_b32_e32 v96, 16, v161
	v_and_b32_e32 v97, 0xffff0000, v161
	v_lshlrev_b32_e32 v98, 16, v162
	v_and_b32_e32 v99, 0xffff0000, v162
	v_lshlrev_b32_e32 v100, 16, v163
	v_and_b32_e32 v101, 0xffff0000, v163
	v_pk_fma_f32 v[68:69], v[124:125], v[94:95], v[68:69]
	v_pk_fma_f32 v[66:67], v[126:127], v[96:97], v[66:67]
	v_pk_fma_f32 v[64:65], v[128:129], v[98:99], v[64:65]
	v_pk_fma_f32 v[62:63], v[130:131], v[100:101], v[62:63]
	s_waitcnt lgkmcnt(5)
	v_lshlrev_b32_e32 v86, 16, v164
	v_and_b32_e32 v87, 0xffff0000, v164
	v_lshlrev_b32_e32 v88, 16, v165
	v_and_b32_e32 v89, 0xffff0000, v165
	v_lshlrev_b32_e32 v90, 16, v166
	v_and_b32_e32 v91, 0xffff0000, v166
	v_lshlrev_b32_e32 v92, 16, v167
	v_and_b32_e32 v93, 0xffff0000, v167
	v_pk_fma_f32 v[52:53], v[124:125], v[86:87], v[52:53]
	v_pk_fma_f32 v[50:51], v[126:127], v[88:89], v[50:51]
	v_pk_fma_f32 v[48:49], v[128:129], v[90:91], v[48:49]
	v_pk_fma_f32 v[46:47], v[130:131], v[92:93], v[46:47]
	s_waitcnt lgkmcnt(4)
	v_lshlrev_b32_e32 v94, 16, v178
	v_and_b32_e32 v95, 0xffff0000, v178
	v_lshlrev_b32_e32 v96, 16, v179
	v_and_b32_e32 v97, 0xffff0000, v179
	v_lshlrev_b32_e32 v98, 16, v180
	v_and_b32_e32 v99, 0xffff0000, v180
	v_lshlrev_b32_e32 v100, 16, v181
	v_and_b32_e32 v101, 0xffff0000, v181
	v_pk_fma_f32 v[30:31], v[124:125], v[94:95], v[30:31]
	v_pk_fma_f32 v[28:29], v[126:127], v[96:97], v[28:29]
	v_pk_fma_f32 v[26:27], v[128:129], v[98:99], v[26:27]
	v_pk_fma_f32 v[24:25], v[130:131], v[100:101], v[24:25]
	s_waitcnt lgkmcnt(3)
	v_lshlrev_b32_e32 v86, 16, v182
	v_and_b32_e32 v87, 0xffff0000, v182
	v_lshlrev_b32_e32 v88, 16, v183
	v_and_b32_e32 v89, 0xffff0000, v183
	v_lshlrev_b32_e32 v90, 16, v184
	v_and_b32_e32 v91, 0xffff0000, v184
	v_lshlrev_b32_e32 v92, 16, v185
	v_and_b32_e32 v93, 0xffff0000, v185
	v_pk_fma_f32 v[6:7], v[132:133], v[86:87], v[6:7]
	v_pk_fma_f32 v[4:5], v[134:135], v[88:89], v[4:5]
	v_pk_fma_f32 v[2:3], v[136:137], v[90:91], v[2:3]
	v_pk_fma_f32 v[0:1], v[138:139], v[92:93], v[0:1]
	s_waitcnt lgkmcnt(2)
	v_lshlrev_b32_e32 v94, 16, v186
	v_and_b32_e32 v95, 0xffff0000, v186
	v_lshlrev_b32_e32 v96, 16, v187
	v_and_b32_e32 v97, 0xffff0000, v187
	v_lshlrev_b32_e32 v98, 16, v188
	v_and_b32_e32 v99, 0xffff0000, v188
	v_lshlrev_b32_e32 v100, 16, v189
	v_and_b32_e32 v101, 0xffff0000, v189
	v_pk_fma_f32 v[60:61], v[132:133], v[94:95], v[60:61]
	v_pk_fma_f32 v[58:59], v[134:135], v[96:97], v[58:59]
	v_pk_fma_f32 v[56:57], v[136:137], v[98:99], v[56:57]
	v_pk_fma_f32 v[54:55], v[138:139], v[100:101], v[54:55]
	s_waitcnt lgkmcnt(1)
	v_lshlrev_b32_e32 v86, 16, v190
	v_and_b32_e32 v87, 0xffff0000, v190
	v_lshlrev_b32_e32 v88, 16, v191
	v_and_b32_e32 v89, 0xffff0000, v191
	v_lshlrev_b32_e32 v90, 16, v192
	v_and_b32_e32 v91, 0xffff0000, v192
	v_lshlrev_b32_e32 v92, 16, v193
	v_and_b32_e32 v93, 0xffff0000, v193
	v_pk_fma_f32 v[44:45], v[132:133], v[86:87], v[44:45]
	v_pk_fma_f32 v[42:43], v[134:135], v[88:89], v[42:43]
	v_pk_fma_f32 v[40:41], v[136:137], v[90:91], v[40:41]
	v_pk_fma_f32 v[38:39], v[138:139], v[92:93], v[38:39]
	s_waitcnt lgkmcnt(0)
	v_lshlrev_b32_e32 v94, 16, v194
	v_and_b32_e32 v95, 0xffff0000, v194
	v_lshlrev_b32_e32 v96, 16, v195
	v_and_b32_e32 v97, 0xffff0000, v195
	v_lshlrev_b32_e32 v98, 16, v196
	v_and_b32_e32 v99, 0xffff0000, v196
	v_lshlrev_b32_e32 v100, 16, v197
	v_and_b32_e32 v101, 0xffff0000, v197
	v_pk_fma_f32 v[22:23], v[132:133], v[94:95], v[22:23]
	v_pk_fma_f32 v[20:21], v[134:135], v[96:97], v[20:21]
	v_pk_fma_f32 v[18:19], v[136:137], v[98:99], v[18:19]
	v_pk_fma_f32 v[16:17], v[138:139], v[100:101], v[16:17]
	v_mov_b32_e32 v72, v73
	v_mov_b64_e32 v[32:33], v[70:71]
	s_waitcnt vmcnt(0)
	v_mov_b64_e32 v[124:125], v[140:141]
	v_mov_b64_e32 v[126:127], v[142:143]
	v_mov_b64_e32 v[128:129], v[144:145]
	v_mov_b64_e32 v[130:131], v[146:147]
	v_mov_b64_e32 v[132:133], v[148:149]
	v_mov_b64_e32 v[134:135], v[150:151]
	v_mov_b64_e32 v[136:137], v[152:153]
	v_mov_b64_e32 v[138:139], v[154:155]
	s_cbranch_scc1 .LBB0_361
	v_lshlrev_b32_e32 v82, 2, v8
	global_load_dwordx4 v[70:73], v82, s[58:59] offset:16
	global_load_dwordx4 v[74:77], v82, s[58:59]
	v_and_b32_e32 v9, -4, v9
	v_add_u32_e32 v32, s1, v9
	v_lshlrev_b32_e32 v168, 1, v8
	s_mov_b64 s[6:7], 0x3000
	s_waitcnt vmcnt(1)
	v_add_f32_e32 v89, v14, v70
	s_waitcnt vmcnt(0)
	v_add_f32_e32 v98, v36, v74
	v_add_f32_e32 v9, 0, v98
	v_add_f32_e32 v97, v37, v75
	v_add_f32_e32 v9, v9, v97
	v_add_f32_e32 v96, v34, v76
	v_add_f32_e32 v9, v9, v96
	v_add_f32_e32 v90, v35, v77
	v_add_f32_e32 v9, v9, v90
	v_add_f32_e32 v9, v9, v89
	v_add_f32_e32 v88, v15, v71
	v_add_f32_e32 v9, v9, v88
	v_add_f32_e32 v77, v12, v72
	v_add_f32_e32 v9, v9, v77
	v_add_f32_e32 v76, v13, v73
	v_add_f32_e32 v33, v9, v76
	global_load_dwordx4 v[8:11], v82, s[58:59] offset:2048
	global_load_dwordx4 v[12:15], v82, s[58:59] offset:2064
	v_mov_b64_e32 v[34:35], s[54:55]
	s_waitcnt vmcnt(1)
	v_add_f32_e32 v87, v6, v8
	v_add_f32_e32 v6, v33, v87
	v_add_f32_e32 v86, v7, v9
	v_add_f32_e32 v6, v6, v86
	v_add_f32_e32 v85, v4, v10
	v_add_f32_e32 v4, v6, v85
	v_add_f32_e32 v84, v5, v11
	v_add_f32_e32 v4, v4, v84
	s_waitcnt vmcnt(0)
	v_pk_add_f32 v[2:3], v[2:3], v[12:13]
	v_pk_add_f32 v[0:1], v[0:1], v[14:15]
	v_add_f32_e32 v4, v4, v2
	v_add_f32_e32 v4, v4, v3
	v_add_f32_e32 v4, v4, v0
	v_add_f32_e32 v4, v4, v1
	ds_bpermute_b32 v5, v121, v4
	v_ashrrev_i32_e32 v33, 31, v32
	s_waitcnt lgkmcnt(0)
	v_add_f32_e32 v4, v4, v5
	ds_bpermute_b32 v5, v119, v4
	s_waitcnt lgkmcnt(0)
	v_add_f32_e32 v4, v4, v5
	ds_bpermute_b32 v5, v78, v4
	s_waitcnt lgkmcnt(0)
	v_add_f32_e32 v4, v4, v5
	ds_bpermute_b32 v5, v79, v4
	s_waitcnt lgkmcnt(0)
	v_add_f32_e32 v4, v4, v5
	ds_bpermute_b32 v5, v80, v4
	s_waitcnt lgkmcnt(0)
	v_add_f32_e32 v4, v4, v5
	ds_bpermute_b32 v5, v81, v4
	s_waitcnt lgkmcnt(0)
	v_add_f32_e32 v5, v4, v5
	v_fmac_f32_e32 v97, 0xba800000, v5
	v_fmac_f32_e32 v98, 0xba800000, v5
	v_mul_f32_e32 v6, v97, v97
	v_fmac_f32_e32 v6, v98, v98
	v_fmac_f32_e32 v96, 0xba800000, v5
	v_fmac_f32_e32 v6, v96, v96
	v_fmac_f32_e32 v90, 0xba800000, v5
	v_fmac_f32_e32 v6, v90, v90
	v_fmac_f32_e32 v89, 0xba800000, v5
	v_fmac_f32_e32 v6, v89, v89
	v_fmac_f32_e32 v88, 0xba800000, v5
	v_fmac_f32_e32 v6, v88, v88
	v_fmac_f32_e32 v77, 0xba800000, v5
	v_fmac_f32_e32 v6, v77, v77
	v_fmac_f32_e32 v76, 0xba800000, v5
	v_fmac_f32_e32 v6, v76, v76
	v_fmac_f32_e32 v87, 0xba800000, v5
	v_fmac_f32_e32 v6, v87, v87
	v_fmac_f32_e32 v86, 0xba800000, v5
	v_mul_f32_e32 v4, 0x3a800000, v5
	v_fmac_f32_e32 v6, v86, v86
	v_fmac_f32_e32 v85, 0xba800000, v5
	v_fmac_f32_e32 v6, v85, v85
	v_fmac_f32_e32 v84, 0xba800000, v5
	v_pk_add_f32 v[72:73], v[2:3], v[4:5] op_sel_hi:[1,0] neg_lo:[0,1] neg_hi:[0,1]
	v_fmac_f32_e32 v6, v84, v84
	v_pk_mul_f32 v[2:3], v[72:73], v[72:73]
	v_pk_add_f32 v[70:71], v[0:1], v[4:5] op_sel_hi:[1,0] neg_lo:[0,1] neg_hi:[0,1]
	v_add_f32_e32 v2, v2, v6
	v_add_f32_e32 v2, v3, v2
	v_pk_mul_f32 v[0:1], v[70:71], v[70:71]
	s_nop 0
	v_add_f32_e32 v0, v0, v2
	v_add_f32_e32 v0, v1, v0
	ds_bpermute_b32 v1, v121, v0
	s_waitcnt lgkmcnt(0)
	v_add_f32_e32 v0, v0, v1
	ds_bpermute_b32 v1, v119, v0
	s_waitcnt lgkmcnt(0)
	v_add_f32_e32 v0, v0, v1
	ds_bpermute_b32 v1, v78, v0
	s_waitcnt lgkmcnt(0)
	v_add_f32_e32 v0, v0, v1
	ds_bpermute_b32 v1, v79, v0
	s_waitcnt lgkmcnt(0)
	v_add_f32_e32 v0, v0, v1
	ds_bpermute_b32 v1, v80, v0
	s_waitcnt lgkmcnt(0)
	v_add_f32_e32 v0, v0, v1
	ds_bpermute_b32 v1, v81, v0
	s_waitcnt lgkmcnt(0)
	v_add_f32_e32 v0, v0, v1
	v_fmamk_f32 v0, v0, 0x3a800000, v211
	v_cmp_gt_f32_e32 vcc, s80, v0
	v_mul_f32_e32 v1, 0x4b800000, v0
	s_nop 0
	v_cndmask_b32_e32 v0, v0, v1, vcc
	v_rsq_f32_e32 v0, v0
	s_nop 0
	v_mul_f32_e32 v1, 0x45800000, v0
	v_cndmask_b32_e32 v83, v0, v1, vcc
	v_mad_i64_i32 v[0:1], s[4:5], v32, s82, v[34:35]
	v_lshl_add_u64 v[74:75], v[0:1], 0, s[6:7]
	v_lshlrev_b64 v[0:1], 11, v[32:33]
	v_lshl_add_u64 v[36:37], s[56:57], 0, v[0:1]
	global_load_dwordx4 v[4:7], v82, s[60:61] offset:16
	global_load_dwordx4 v[12:15], v82, s[60:61]
	global_load_dwordx4 v[0:3], v82, s[62:63] offset:16
	global_load_dwordx4 v[8:11], v82, s[62:63]
	v_lshl_add_u64 v[92:93], v[74:75], 0, v[168:169]
	global_load_dwordx4 v[100:103], v[92:93], off
	v_mul_f32_e32 v98, v98, v83
	v_mul_f32_e32 v87, v87, v83
	s_waitcnt vmcnt(1)
	v_fma_f32 v8, v12, v98, v8
	v_mul_f32_e32 v12, 0xbfb8aa3b, v8
	v_exp_f32_e32 v12, v12
	s_waitcnt vmcnt(0)
	v_lshlrev_b32_e32 v95, 16, v101
	v_and_b32_e32 v94, 0xffff0000, v101
	v_lshlrev_b32_e32 v93, 16, v102
	v_add_f32_e32 v12, 1.0, v12
	v_and_b32_e32 v92, 0xffff0000, v102
	v_lshlrev_b32_e32 v91, 16, v103
	v_and_b32_e32 v33, 0xffff0000, v103
	v_lshlrev_b32_e32 v99, 16, v100
	v_rcp_f32_e32 v12, v12
	s_nop 0
	s_nop 0
	v_mul_f32_e32 v8, v8, v12
	v_mul_f32_e32 v12, 0xbfb8aa3b, v99
	v_exp_f32_e32 v12, v12
	v_and_b32_e32 v100, 0xffff0000, v100
	v_add_f32_e32 v12, 1.0, v12
	v_div_scale_f32 v98, s[4:5], v12, v12, 1.0
	v_rcp_f32_e32 v101, v98
	s_nop 0
	v_fma_f32 v102, -v98, v101, 1.0
	v_fmac_f32_e32 v101, v102, v101
	v_div_scale_f32 v102, vcc, 1.0, v12, 1.0
	v_mul_f32_e32 v103, v102, v101
	v_fma_f32 v104, -v98, v103, v102
	v_fmac_f32_e32 v103, v104, v101
	v_rcp_f32_e32 v12, v12
	s_nop 0
	s_nop 0
	v_mul_f32_e32 v12, v12, v99
	v_mul_f32_e32 v8, v12, v8
	v_mul_f32_e32 v12, v97, v83
	v_fma_f32 v9, v13, v12, v9
	v_mul_f32_e32 v12, 0xbfb8aa3b, v9
	v_exp_f32_e32 v12, v12
	s_nop 0
	v_add_f32_e32 v12, 1.0, v12
	s_nop 0
	v_rcp_f32_e32 v12, v12
	s_nop 0
	s_nop 0
	v_mul_f32_e32 v9, v9, v12
	v_mul_f32_e32 v12, 0xbfb8aa3b, v100
	v_exp_f32_e32 v12, v12
	s_nop 0
	v_add_f32_e32 v12, 1.0, v12
	v_div_scale_f32 v13, s[4:5], v12, v12, 1.0
	v_rcp_f32_e32 v97, v13
	s_nop 0
	v_fma_f32 v98, -v13, v97, 1.0
	v_fmac_f32_e32 v97, v98, v97
	v_div_scale_f32 v98, vcc, 1.0, v12, 1.0
	v_mul_f32_e32 v99, v98, v97
	v_fma_f32 v101, -v13, v99, v98
	v_fmac_f32_e32 v99, v101, v97
	v_rcp_f32_e32 v12, v12
	s_nop 0
	s_nop 0
	v_mul_f32_e32 v12, v12, v100
	v_mul_f32_e32 v9, v12, v9
	v_mul_f32_e32 v12, v96, v83
	v_fma_f32 v10, v14, v12, v10
	v_mul_f32_e32 v12, 0xbfb8aa3b, v10
	v_exp_f32_e32 v12, v12
	s_nop 0
	v_add_f32_e32 v12, 1.0, v12
	s_nop 0
	v_rcp_f32_e32 v12, v12
	s_nop 0
	s_nop 0
	v_mul_f32_e32 v10, v10, v12
	v_mul_f32_e32 v12, 0xbfb8aa3b, v95
	v_exp_f32_e32 v12, v12
	s_nop 0
	v_add_f32_e32 v12, 1.0, v12
	v_div_scale_f32 v13, s[4:5], v12, v12, 1.0
	v_rcp_f32_e32 v14, v13
	s_nop 0
	v_fma_f32 v96, -v13, v14, 1.0
	v_fmac_f32_e32 v14, v96, v14
	v_div_scale_f32 v96, vcc, 1.0, v12, 1.0
	v_mul_f32_e32 v97, v96, v14
	v_fma_f32 v98, -v13, v97, v96
	v_fmac_f32_e32 v97, v98, v14
	v_rcp_f32_e32 v12, v12
	s_nop 0
	s_nop 0
	v_mul_f32_e32 v12, v12, v95
	v_mul_f32_e32 v10, v12, v10
	v_mul_f32_e32 v12, v90, v83
	v_fmac_f32_e32 v11, v15, v12
	v_mul_f32_e32 v12, 0xbfb8aa3b, v11
	v_exp_f32_e32 v12, v12
	s_nop 0
	v_add_f32_e32 v12, 1.0, v12
	s_nop 0
	v_rcp_f32_e32 v12, v12
	s_nop 0
	s_nop 0
	v_mul_f32_e32 v11, v11, v12
	v_mul_f32_e32 v12, 0xbfb8aa3b, v94
	v_exp_f32_e32 v12, v12
	s_nop 0
	v_add_f32_e32 v12, 1.0, v12
	s_nop 0
	v_rcp_f32_e32 v12, v12
	s_nop 0
	s_nop 0
	v_mul_f32_e32 v12, v12, v94
	v_mul_f32_e32 v11, v12, v11
	v_mul_f32_e32 v12, v89, v83
	v_fma_f32 v0, v4, v12, v0
	v_mul_f32_e32 v4, 0xbfb8aa3b, v0
	v_exp_f32_e32 v4, v4
	s_nop 0
	v_add_f32_e32 v4, 1.0, v4
	s_nop 0
	v_rcp_f32_e32 v4, v4
	s_nop 0
	s_nop 0
	v_mul_f32_e32 v0, v0, v4
	v_mul_f32_e32 v4, 0xbfb8aa3b, v93
	v_exp_f32_e32 v4, v4
	s_nop 0
	v_add_f32_e32 v4, 1.0, v4
	s_nop 0
	v_rcp_f32_e32 v4, v4
	s_nop 0
	s_nop 0
	v_mul_f32_e32 v4, v4, v93
	v_mul_f32_e32 v4, v4, v0
	v_mul_f32_e32 v0, v88, v83
	v_fma_f32 v0, v5, v0, v1
	v_mul_f32_e32 v1, 0xbfb8aa3b, v0
	v_exp_f32_e32 v1, v1
	s_nop 0
	v_add_f32_e32 v1, 1.0, v1
	s_nop 0
	v_rcp_f32_e32 v1, v1
	s_nop 0
	s_nop 0
	v_mul_f32_e32 v0, v0, v1
	v_mul_f32_e32 v1, 0xbfb8aa3b, v92
	v_exp_f32_e32 v1, v1
	s_nop 0
	v_add_f32_e32 v1, 1.0, v1
	s_nop 0
	v_rcp_f32_e32 v1, v1
	s_nop 0
	s_nop 0
	v_mul_f32_e32 v1, v1, v92
	v_mul_f32_e32 v5, v1, v0
	v_mul_f32_e32 v0, v77, v83
	v_fma_f32 v0, v6, v0, v2
	v_mul_f32_e32 v1, 0xbfb8aa3b, v0
	v_exp_f32_e32 v1, v1
	s_nop 0
	v_add_f32_e32 v1, 1.0, v1
	s_nop 0
	v_rcp_f32_e32 v1, v1
	s_nop 0
	s_nop 0
	v_mul_f32_e32 v0, v0, v1
	v_mul_f32_e32 v1, 0xbfb8aa3b, v91
	v_exp_f32_e32 v1, v1
	s_nop 0
	v_add_f32_e32 v1, 1.0, v1
	s_nop 0
	v_rcp_f32_e32 v1, v1
	s_nop 0
	s_nop 0
	v_mul_f32_e32 v1, v1, v91
	v_mul_f32_e32 v6, v1, v0
	v_mul_f32_e32 v0, v76, v83
	v_fmac_f32_e32 v3, v7, v0
	v_mul_f32_e32 v0, 0xbfb8aa3b, v3
	v_exp_f32_e32 v0, v0
	v_lshl_add_u64 v[76:77], v[36:37], 0, v[168:169]
	v_or_b32_e32 v36, 0x400, v168
	v_mov_b32_e32 v37, v169
	v_add_f32_e32 v0, 1.0, v0
	v_lshl_add_u64 v[74:75], v[74:75], 0, v[36:37]
	v_rcp_f32_e32 v0, v0
	s_nop 0
	v_mul_f32_e32 v1, 0xbfb8aa3b, v33
	v_exp_f32_e32 v1, v1
	v_mul_f32_e32 v0, v3, v0
	v_add_f32_e32 v1, 1.0, v1
	s_nop 0
	v_rcp_f32_e32 v1, v1
	s_nop 0
	s_nop 0
	v_mul_f32_e32 v1, v1, v33
	v_mul_f32_e32 v3, v1, v0
	v_cvt_pk_bf16_f32 v0, v8, v9
	v_cvt_pk_bf16_f32 v1, v10, v11
	v_cvt_pk_bf16_f32 v2, v4, v5
	v_cvt_pk_bf16_f32 v3, v6, v3
	global_store_dwordx4 v[76:77], v[0:3], off
	global_load_dwordx4 v[4:7], v82, s[60:61] offset:2064
	global_load_dwordx4 v[12:15], v82, s[60:61] offset:2048
	s_nop 0
	global_load_dwordx4 v[0:3], v82, s[62:63] offset:2064
	global_load_dwordx4 v[8:11], v82, s[62:63] offset:2048
	global_load_dwordx4 v[88:91], v[74:75], off
	s_waitcnt vmcnt(1)
	v_fma_f32 v8, v87, v12, v8
	v_mul_f32_e32 v12, 0xbfb8aa3b, v8
	v_exp_f32_e32 v12, v12
	s_waitcnt vmcnt(0)
	v_lshlrev_b32_e32 v92, 16, v88
	v_and_b32_e32 v93, 0xffff0000, v88
	v_lshlrev_b32_e32 v88, 16, v90
	v_add_f32_e32 v12, 1.0, v12
	v_and_b32_e32 v75, 0xffff0000, v90
	v_lshlrev_b32_e32 v74, 16, v91
	v_and_b32_e32 v33, 0xffff0000, v91
	v_lshlrev_b32_e32 v94, 16, v89
	v_rcp_f32_e32 v12, v12
	s_nop 0
	s_nop 0
	v_mul_f32_e32 v8, v8, v12
	v_mul_f32_e32 v12, 0xbfb8aa3b, v92
	v_exp_f32_e32 v12, v12
	v_and_b32_e32 v89, 0xffff0000, v89
	v_add_f32_e32 v12, 1.0, v12
	v_div_scale_f32 v87, s[4:5], v12, v12, 1.0
	v_rcp_f32_e32 v90, v87
	s_nop 0
	v_fma_f32 v91, -v87, v90, 1.0
	v_fmac_f32_e32 v90, v91, v90
	v_div_scale_f32 v91, vcc, 1.0, v12, 1.0
	v_mul_f32_e32 v95, v91, v90
	v_fma_f32 v96, -v87, v95, v91
	v_fmac_f32_e32 v95, v96, v90
	v_rcp_f32_e32 v12, v12
	s_nop 0
	s_nop 0
	v_mul_f32_e32 v12, v12, v92
	v_mul_f32_e32 v8, v8, v12
	v_mul_f32_e32 v12, v86, v83
	v_fma_f32 v9, v12, v13, v9
	v_mul_f32_e32 v12, 0xbfb8aa3b, v9
	v_exp_f32_e32 v12, v12
	s_nop 0
	v_add_f32_e32 v12, 1.0, v12
	s_nop 0
	v_rcp_f32_e32 v12, v12
	s_nop 0
	s_nop 0
	v_mul_f32_e32 v9, v9, v12
	v_mul_f32_e32 v12, 0xbfb8aa3b, v93
	v_exp_f32_e32 v12, v12
	s_nop 0
	v_add_f32_e32 v12, 1.0, v12
	v_div_scale_f32 v13, s[4:5], v12, v12, 1.0
	v_rcp_f32_e32 v86, v13
	s_nop 0
	v_fma_f32 v87, -v13, v86, 1.0
	v_fmac_f32_e32 v86, v87, v86
	v_div_scale_f32 v87, vcc, 1.0, v12, 1.0
	v_mul_f32_e32 v90, v87, v86
	v_fma_f32 v91, -v13, v90, v87
	v_rcp_f32_e32 v12, v12
	s_nop 0
	s_nop 0
	v_mul_f32_e32 v12, v12, v93
	v_mul_f32_e32 v9, v9, v12
	v_mul_f32_e32 v12, v85, v83
	v_fma_f32 v10, v12, v14, v10
	v_mul_f32_e32 v12, 0xbfb8aa3b, v10
	v_exp_f32_e32 v12, v12
	s_nop 0
	v_add_f32_e32 v12, 1.0, v12
	s_nop 0
	v_rcp_f32_e32 v12, v12
	s_nop 0
	s_nop 0
	v_mul_f32_e32 v10, v10, v12
	v_mul_f32_e32 v12, 0xbfb8aa3b, v94
	v_exp_f32_e32 v12, v12
	s_nop 0
	v_add_f32_e32 v12, 1.0, v12
	s_nop 0
	v_rcp_f32_e32 v12, v12
	s_nop 0
	s_nop 0
	v_mul_f32_e32 v12, v12, v94
	v_mul_f32_e32 v10, v10, v12
	v_mul_f32_e32 v12, v84, v83
	v_fmac_f32_e32 v11, v12, v15
	v_mul_f32_e32 v12, 0xbfb8aa3b, v11
	v_exp_f32_e32 v12, v12
	s_nop 0
	v_add_f32_e32 v12, 1.0, v12
	s_nop 0
	v_rcp_f32_e32 v12, v12
	s_nop 0
	s_nop 0
	v_mul_f32_e32 v11, v11, v12
	v_mul_f32_e32 v12, 0xbfb8aa3b, v89
	v_exp_f32_e32 v12, v12
	s_nop 0
	v_add_f32_e32 v12, 1.0, v12
	s_nop 0
	v_rcp_f32_e32 v12, v12
	s_nop 0
	s_nop 0
	v_mul_f32_e32 v12, v12, v89
	v_mul_f32_e32 v11, v11, v12
	v_mul_f32_e32 v12, v72, v83
	v_fma_f32 v0, v12, v4, v0
	v_mul_f32_e32 v4, 0xbfb8aa3b, v0
	v_exp_f32_e32 v4, v4
	s_nop 0
	v_add_f32_e32 v4, 1.0, v4
	s_nop 0
	v_rcp_f32_e32 v4, v4
	s_nop 0
	s_nop 0
	v_mul_f32_e32 v0, v0, v4
	v_mul_f32_e32 v4, 0xbfb8aa3b, v88
	v_exp_f32_e32 v4, v4
	s_nop 0
	v_add_f32_e32 v4, 1.0, v4
	s_nop 0
	v_rcp_f32_e32 v4, v4
	s_nop 0
	s_nop 0
	v_mul_f32_e32 v4, v4, v88
	v_mul_f32_e32 v4, v0, v4
	v_mul_f32_e32 v0, v73, v83
	v_fma_f32 v0, v0, v5, v1
	v_mul_f32_e32 v1, 0xbfb8aa3b, v0
	v_exp_f32_e32 v1, v1
	s_nop 0
	v_add_f32_e32 v1, 1.0, v1
	s_nop 0
	v_rcp_f32_e32 v1, v1
	s_nop 0
	s_nop 0
	v_mul_f32_e32 v0, v0, v1
	v_mul_f32_e32 v1, 0xbfb8aa3b, v75
	v_exp_f32_e32 v1, v1
	s_nop 0
	v_add_f32_e32 v1, 1.0, v1
	s_nop 0
	v_rcp_f32_e32 v1, v1
	s_nop 0
	s_nop 0
	v_mul_f32_e32 v1, v1, v75
	v_mul_f32_e32 v5, v0, v1
	v_mul_f32_e32 v0, v70, v83
	v_fma_f32 v0, v0, v6, v2
	v_mul_f32_e32 v1, 0xbfb8aa3b, v0
	v_exp_f32_e32 v1, v1
	s_nop 0
	v_add_f32_e32 v1, 1.0, v1
	s_nop 0
	v_rcp_f32_e32 v1, v1
	s_nop 0
	s_nop 0
	v_mul_f32_e32 v0, v0, v1
	v_mul_f32_e32 v1, 0xbfb8aa3b, v74
	v_exp_f32_e32 v1, v1
	s_nop 0
	v_add_f32_e32 v1, 1.0, v1
	s_nop 0
	v_rcp_f32_e32 v1, v1
	s_nop 0
	s_nop 0
	v_mul_f32_e32 v1, v1, v74
	v_mul_f32_e32 v6, v0, v1
	v_mul_f32_e32 v0, v71, v83
	v_fmac_f32_e32 v3, v0, v7
	v_mul_f32_e32 v0, 0xbfb8aa3b, v3
	v_exp_f32_e32 v0, v0
	s_nop 0
	v_add_f32_e32 v0, 1.0, v0
	s_nop 0
	v_rcp_f32_e32 v0, v0
	s_nop 0
	v_mul_f32_e32 v1, 0xbfb8aa3b, v33
	v_exp_f32_e32 v1, v1
	v_mul_f32_e32 v0, v3, v0
	v_add_f32_e32 v1, 1.0, v1
	s_nop 0
	v_rcp_f32_e32 v1, v1
	s_nop 0
	s_nop 0
	v_mul_f32_e32 v1, v1, v33
	v_mul_f32_e32 v3, v0, v1
	v_cvt_pk_bf16_f32 v0, v8, v9
	v_cvt_pk_bf16_f32 v1, v10, v11
	v_cvt_pk_bf16_f32 v2, v4, v5
	v_cvt_pk_bf16_f32 v3, v6, v3
	global_store_dwordx4 v[76:77], v[0:3], off offset:1024
	global_load_dwordx4 v[0:3], v82, s[58:59] offset:16
	s_nop 0
	global_load_dwordx4 v[4:7], v82, s[58:59]
	s_waitcnt vmcnt(0)
	v_add_f32_e32 v76, v68, v4
	v_add_f32_e32 v4, 0, v76
	v_add_f32_e32 v74, v69, v5
	v_add_f32_e32 v4, v4, v74
	v_add_f32_e32 v72, v66, v6
	v_add_f32_e32 v4, v4, v72
	v_add_f32_e32 v70, v67, v7
	v_add_f32_e32 v4, v4, v70
	v_add_f32_e32 v69, v64, v0
	v_add_f32_e32 v0, v4, v69
	v_add_f32_e32 v68, v65, v1
	v_add_f32_e32 v0, v0, v68
	v_add_f32_e32 v67, v62, v2
	v_add_f32_e32 v0, v0, v67
	v_add_f32_e32 v66, v63, v3
	v_add_f32_e32 v8, v0, v66
	global_load_dwordx4 v[0:3], v82, s[58:59] offset:2048
	global_load_dwordx4 v[4:7], v82, s[58:59] offset:2064
	s_waitcnt vmcnt(1)
	v_add_f32_e32 v65, v60, v0
	v_add_f32_e32 v0, v8, v65
	v_add_f32_e32 v64, v61, v1
	v_add_f32_e32 v0, v0, v64
	v_add_f32_e32 v63, v58, v2
	v_add_f32_e32 v0, v0, v63
	v_add_f32_e32 v62, v59, v3
	v_add_f32_e32 v8, v0, v62
	s_waitcnt vmcnt(0)
	v_pk_add_f32 v[2:3], v[56:57], v[4:5]
	v_pk_add_f32 v[0:1], v[54:55], v[6:7]
	v_add_f32_e32 v4, v8, v2
	v_add_f32_e32 v4, v4, v3
	v_add_f32_e32 v4, v4, v0
	v_add_f32_e32 v4, v4, v1
	ds_bpermute_b32 v5, v121, v4
	s_waitcnt lgkmcnt(0)
	v_add_f32_e32 v4, v4, v5
	ds_bpermute_b32 v5, v119, v4
	s_waitcnt lgkmcnt(0)
	v_add_f32_e32 v4, v4, v5
	ds_bpermute_b32 v5, v78, v4
	s_waitcnt lgkmcnt(0)
	v_add_f32_e32 v4, v4, v5
	ds_bpermute_b32 v5, v79, v4
	s_waitcnt lgkmcnt(0)
	v_add_f32_e32 v4, v4, v5
	ds_bpermute_b32 v5, v80, v4
	s_waitcnt lgkmcnt(0)
	v_add_f32_e32 v4, v4, v5
	ds_bpermute_b32 v5, v81, v4
	s_waitcnt lgkmcnt(0)
	v_add_f32_e32 v5, v4, v5
	v_fmac_f32_e32 v74, 0xba800000, v5
	v_fmac_f32_e32 v76, 0xba800000, v5
	v_mul_f32_e32 v6, v74, v74
	v_fmac_f32_e32 v6, v76, v76
	v_fmac_f32_e32 v72, 0xba800000, v5
	v_fmac_f32_e32 v6, v72, v72
	v_fmac_f32_e32 v70, 0xba800000, v5
	v_fmac_f32_e32 v6, v70, v70
	v_fmac_f32_e32 v69, 0xba800000, v5
	v_fmac_f32_e32 v6, v69, v69
	v_fmac_f32_e32 v68, 0xba800000, v5
	v_fmac_f32_e32 v6, v68, v68
	v_fmac_f32_e32 v67, 0xba800000, v5
	v_fmac_f32_e32 v6, v67, v67
	v_fmac_f32_e32 v66, 0xba800000, v5
	v_fmac_f32_e32 v6, v66, v66
	v_fmac_f32_e32 v65, 0xba800000, v5
	v_fmac_f32_e32 v6, v65, v65
	v_fmac_f32_e32 v64, 0xba800000, v5
	v_mul_f32_e32 v4, 0x3a800000, v5
	v_fmac_f32_e32 v6, v64, v64
	v_fmac_f32_e32 v63, 0xba800000, v5
	v_fmac_f32_e32 v6, v63, v63
	v_fmac_f32_e32 v62, 0xba800000, v5
	v_pk_add_f32 v[56:57], v[2:3], v[4:5] op_sel_hi:[1,0] neg_lo:[0,1] neg_hi:[0,1]
	v_fmac_f32_e32 v6, v62, v62
	v_pk_mul_f32 v[2:3], v[56:57], v[56:57]
	v_pk_add_f32 v[54:55], v[0:1], v[4:5] op_sel_hi:[1,0] neg_lo:[0,1] neg_hi:[0,1]
	v_add_f32_e32 v2, v2, v6
	v_add_f32_e32 v2, v3, v2
	v_pk_mul_f32 v[0:1], v[54:55], v[54:55]
	s_nop 0
	v_add_f32_e32 v0, v0, v2
	v_add_f32_e32 v1, v1, v0
	ds_bpermute_b32 v2, v121, v1
	v_or_b32_e32 v0, 1, v32
	s_waitcnt lgkmcnt(0)
	v_add_f32_e32 v1, v1, v2
	ds_bpermute_b32 v2, v119, v1
	s_waitcnt lgkmcnt(0)
	v_add_f32_e32 v1, v1, v2
	ds_bpermute_b32 v2, v78, v1
	s_waitcnt lgkmcnt(0)
	v_add_f32_e32 v1, v1, v2
	ds_bpermute_b32 v2, v79, v1
	s_waitcnt lgkmcnt(0)
	v_add_f32_e32 v1, v1, v2
	ds_bpermute_b32 v2, v80, v1
	s_waitcnt lgkmcnt(0)
	v_add_f32_e32 v1, v1, v2
	ds_bpermute_b32 v2, v81, v1
	s_waitcnt lgkmcnt(0)
	v_add_f32_e32 v1, v1, v2
	v_fmamk_f32 v1, v1, 0x3a800000, v211
	v_cmp_gt_f32_e32 vcc, s80, v1
	v_mul_f32_e32 v2, 0x4b800000, v1
	s_nop 0
	v_cndmask_b32_e32 v1, v1, v2, vcc
	v_rsq_f32_e32 v1, v1
	s_nop 0
	v_mul_f32_e32 v2, 0x45800000, v1
	v_cndmask_b32_e32 v33, v1, v2, vcc
	v_ashrrev_i32_e32 v1, 31, v0
	v_mad_i64_i32 v[2:3], s[4:5], v0, s82, v[34:35]
	v_lshlrev_b64 v[0:1], 11, v[0:1]
	v_lshl_add_u64 v[58:59], v[2:3], 0, s[6:7]
	v_lshl_add_u64 v[60:61], s[56:57], 0, v[0:1]
	global_load_dwordx4 v[4:7], v82, s[60:61] offset:16
	global_load_dwordx4 v[12:15], v82, s[60:61]
	global_load_dwordx4 v[0:3], v82, s[62:63] offset:16
	global_load_dwordx4 v[8:11], v82, s[62:63]
	v_lshl_add_u64 v[84:85], v[58:59], 0, v[168:169]
	global_load_dwordx4 v[84:87], v[84:85], off
	v_mul_f32_e32 v76, v76, v33
	v_lshl_add_u64 v[60:61], v[60:61], 0, v[168:169]
	v_lshl_add_u64 v[58:59], v[58:59], 0, v[36:37]
	v_mul_f32_e32 v65, v65, v33
	s_waitcnt vmcnt(1)
	v_fma_f32 v8, v12, v76, v8
	v_mul_f32_e32 v12, 0xbfb8aa3b, v8
	v_exp_f32_e32 v12, v12
	s_waitcnt vmcnt(0)
	v_lshlrev_b32_e32 v89, 16, v85
	v_and_b32_e32 v83, 0xffff0000, v85
	v_lshlrev_b32_e32 v77, 16, v86
	v_add_f32_e32 v12, 1.0, v12
	v_and_b32_e32 v75, 0xffff0000, v86
	v_lshlrev_b32_e32 v73, 16, v87
	v_and_b32_e32 v71, 0xffff0000, v87
	v_lshlrev_b32_e32 v88, 16, v84
	v_rcp_f32_e32 v12, v12
	s_nop 0
	s_nop 0
	v_mul_f32_e32 v8, v8, v12
	v_mul_f32_e32 v12, 0xbfb8aa3b, v88
	v_exp_f32_e32 v12, v12
	v_and_b32_e32 v84, 0xffff0000, v84
	v_add_f32_e32 v12, 1.0, v12
	v_div_scale_f32 v76, s[4:5], v12, v12, 1.0
	v_rcp_f32_e32 v85, v76
	s_nop 0
	v_fma_f32 v86, -v76, v85, 1.0
	v_fmac_f32_e32 v85, v86, v85
	v_div_scale_f32 v86, vcc, 1.0, v12, 1.0
	v_mul_f32_e32 v87, v86, v85
	v_fma_f32 v90, -v76, v87, v86
	v_fmac_f32_e32 v87, v90, v85
	v_rcp_f32_e32 v12, v12
	s_nop 0
	s_nop 0
	v_mul_f32_e32 v12, v12, v88
	v_mul_f32_e32 v8, v12, v8
	v_mul_f32_e32 v12, v74, v33
	v_fma_f32 v9, v13, v12, v9
	v_mul_f32_e32 v12, 0xbfb8aa3b, v9
	v_exp_f32_e32 v12, v12
	s_nop 0
	v_add_f32_e32 v12, 1.0, v12
	s_nop 0
	v_rcp_f32_e32 v12, v12
	s_nop 0
	s_nop 0
	v_mul_f32_e32 v9, v9, v12
	v_mul_f32_e32 v12, 0xbfb8aa3b, v84
	v_exp_f32_e32 v12, v12
	s_nop 0
	v_add_f32_e32 v12, 1.0, v12
	v_div_scale_f32 v13, s[4:5], v12, v12, 1.0
	v_rcp_f32_e32 v74, v13
	s_nop 0
	v_fma_f32 v76, -v13, v74, 1.0
	v_fmac_f32_e32 v74, v76, v74
	v_div_scale_f32 v76, vcc, 1.0, v12, 1.0
	v_mul_f32_e32 v85, v76, v74
	v_fma_f32 v86, -v13, v85, v76
	v_fmac_f32_e32 v85, v86, v74
	v_rcp_f32_e32 v12, v12
	s_nop 0
	s_nop 0
	v_mul_f32_e32 v12, v12, v84
	v_mul_f32_e32 v9, v12, v9
	v_mul_f32_e32 v12, v72, v33
	v_fma_f32 v10, v14, v12, v10
	v_mul_f32_e32 v12, 0xbfb8aa3b, v10
	v_exp_f32_e32 v12, v12
	s_nop 0
	v_add_f32_e32 v12, 1.0, v12
	s_nop 0
	v_rcp_f32_e32 v12, v12
	s_nop 0
	s_nop 0
	v_mul_f32_e32 v10, v10, v12
	v_mul_f32_e32 v12, 0xbfb8aa3b, v89
	v_exp_f32_e32 v12, v12
	s_nop 0
	v_add_f32_e32 v12, 1.0, v12
	v_div_scale_f32 v13, s[4:5], v12, v12, 1.0
	v_rcp_f32_e32 v14, v13
	s_nop 0
	v_fma_f32 v72, -v13, v14, 1.0
	v_fmac_f32_e32 v14, v72, v14
	v_div_scale_f32 v72, vcc, 1.0, v12, 1.0
	v_mul_f32_e32 v74, v72, v14
	v_fma_f32 v76, -v13, v74, v72
	v_rcp_f32_e32 v12, v12
	s_nop 0
	s_nop 0
	v_mul_f32_e32 v12, v12, v89
	v_mul_f32_e32 v10, v12, v10
	v_mul_f32_e32 v12, v70, v33
	v_fmac_f32_e32 v11, v15, v12
	v_mul_f32_e32 v12, 0xbfb8aa3b, v11
	v_exp_f32_e32 v12, v12
	s_nop 0
	v_add_f32_e32 v12, 1.0, v12
	s_nop 0
	v_rcp_f32_e32 v12, v12
	s_nop 0
	s_nop 0
	v_mul_f32_e32 v11, v11, v12
	v_mul_f32_e32 v12, 0xbfb8aa3b, v83
	v_exp_f32_e32 v12, v12
	s_nop 0
	v_add_f32_e32 v12, 1.0, v12
	s_nop 0
	v_rcp_f32_e32 v12, v12
	s_nop 0
	s_nop 0
	v_mul_f32_e32 v12, v12, v83
	v_mul_f32_e32 v11, v12, v11
	v_mul_f32_e32 v12, v69, v33
	v_fma_f32 v0, v4, v12, v0
	v_mul_f32_e32 v4, 0xbfb8aa3b, v0
	v_exp_f32_e32 v4, v4
	s_nop 0
	v_add_f32_e32 v4, 1.0, v4
	s_nop 0
	v_rcp_f32_e32 v4, v4
	s_nop 0
	s_nop 0
	v_mul_f32_e32 v0, v0, v4
	v_mul_f32_e32 v4, 0xbfb8aa3b, v77
	v_exp_f32_e32 v4, v4
	s_nop 0
	v_add_f32_e32 v4, 1.0, v4
	s_nop 0
	v_rcp_f32_e32 v4, v4
	s_nop 0
	s_nop 0
	v_mul_f32_e32 v4, v4, v77
	v_mul_f32_e32 v4, v4, v0
	v_mul_f32_e32 v0, v68, v33
	v_fma_f32 v0, v5, v0, v1
	v_mul_f32_e32 v1, 0xbfb8aa3b, v0
	v_exp_f32_e32 v1, v1
	s_nop 0
	v_add_f32_e32 v1, 1.0, v1
	s_nop 0
	v_rcp_f32_e32 v1, v1
	s_nop 0
	s_nop 0
	v_mul_f32_e32 v0, v0, v1
	v_mul_f32_e32 v1, 0xbfb8aa3b, v75
	v_exp_f32_e32 v1, v1
	s_nop 0
	v_add_f32_e32 v1, 1.0, v1
	s_nop 0
	v_rcp_f32_e32 v1, v1
	s_nop 0
	s_nop 0
	v_mul_f32_e32 v1, v1, v75
	v_mul_f32_e32 v5, v1, v0
	v_mul_f32_e32 v0, v67, v33
	v_fma_f32 v0, v6, v0, v2
	v_mul_f32_e32 v1, 0xbfb8aa3b, v0
	v_exp_f32_e32 v1, v1
	s_nop 0
	v_add_f32_e32 v1, 1.0, v1
	s_nop 0
	v_rcp_f32_e32 v1, v1
	s_nop 0
	s_nop 0
	v_mul_f32_e32 v0, v0, v1
	v_mul_f32_e32 v1, 0xbfb8aa3b, v73
	v_exp_f32_e32 v1, v1
	s_nop 0
	v_add_f32_e32 v1, 1.0, v1
	s_nop 0
	v_rcp_f32_e32 v1, v1
	s_nop 0
	s_nop 0
	v_mul_f32_e32 v1, v1, v73
	v_mul_f32_e32 v6, v1, v0
	v_mul_f32_e32 v0, v66, v33
	v_fmac_f32_e32 v3, v7, v0
	v_mul_f32_e32 v0, 0xbfb8aa3b, v3
	v_exp_f32_e32 v0, v0
	s_nop 0
	v_add_f32_e32 v0, 1.0, v0
	s_nop 0
	v_rcp_f32_e32 v0, v0
	s_nop 0
	v_mul_f32_e32 v1, 0xbfb8aa3b, v71
	v_exp_f32_e32 v1, v1
	v_mul_f32_e32 v0, v3, v0
	v_add_f32_e32 v1, 1.0, v1
	s_nop 0
	v_rcp_f32_e32 v1, v1
	s_nop 0
	s_nop 0
	v_mul_f32_e32 v1, v1, v71
	v_mul_f32_e32 v3, v1, v0
	v_cvt_pk_bf16_f32 v0, v8, v9
	v_cvt_pk_bf16_f32 v1, v10, v11
	v_cvt_pk_bf16_f32 v2, v4, v5
	v_cvt_pk_bf16_f32 v3, v6, v3
	global_store_dwordx4 v[60:61], v[0:3], off
	global_load_dwordx4 v[4:7], v82, s[60:61] offset:2064
	global_load_dwordx4 v[12:15], v82, s[60:61] offset:2048
	s_nop 0
	global_load_dwordx4 v[0:3], v82, s[62:63] offset:2064
	global_load_dwordx4 v[8:11], v82, s[62:63] offset:2048
	global_load_dwordx4 v[68:71], v[58:59], off
	s_waitcnt vmcnt(1)
	v_fma_f32 v8, v65, v12, v8
	v_mul_f32_e32 v12, 0xbfb8aa3b, v8
	v_exp_f32_e32 v12, v12
	s_waitcnt vmcnt(0)
	v_lshlrev_b32_e32 v72, 16, v68
	v_and_b32_e32 v73, 0xffff0000, v68
	v_lshlrev_b32_e32 v74, 16, v69
	v_add_f32_e32 v12, 1.0, v12
	v_and_b32_e32 v68, 0xffff0000, v69
	v_lshlrev_b32_e32 v67, 16, v70
	v_and_b32_e32 v66, 0xffff0000, v70
	v_lshlrev_b32_e32 v59, 16, v71
	v_and_b32_e32 v58, 0xffff0000, v71
	v_rcp_f32_e32 v12, v12
	s_nop 0
	s_nop 0
	v_mul_f32_e32 v8, v8, v12
	v_mul_f32_e32 v12, 0xbfb8aa3b, v72
	v_exp_f32_e32 v12, v12
	s_nop 0
	v_add_f32_e32 v12, 1.0, v12
	v_div_scale_f32 v65, s[4:5], v12, v12, 1.0
	v_rcp_f32_e32 v69, v65
	s_nop 0
	v_fma_f32 v70, -v65, v69, 1.0
	v_fmac_f32_e32 v69, v70, v69
	v_div_scale_f32 v70, vcc, 1.0, v12, 1.0
	v_mul_f32_e32 v71, v70, v69
	v_fma_f32 v75, -v65, v71, v70
	v_fmac_f32_e32 v71, v75, v69
	v_rcp_f32_e32 v12, v12
	s_nop 0
	s_nop 0
	v_mul_f32_e32 v12, v12, v72
	v_mul_f32_e32 v8, v8, v12
	v_mul_f32_e32 v12, v64, v33
	v_fma_f32 v9, v12, v13, v9
	v_mul_f32_e32 v12, 0xbfb8aa3b, v9
	v_exp_f32_e32 v12, v12
	s_nop 0
	v_add_f32_e32 v12, 1.0, v12
	s_nop 0
	v_rcp_f32_e32 v12, v12
	s_nop 0
	s_nop 0
	v_mul_f32_e32 v9, v9, v12
	v_mul_f32_e32 v12, 0xbfb8aa3b, v73
	v_exp_f32_e32 v12, v12
	s_nop 0
	v_add_f32_e32 v12, 1.0, v12
	v_div_scale_f32 v13, s[4:5], v12, v12, 1.0
	v_rcp_f32_e32 v64, v13
	s_nop 0
	v_fma_f32 v65, -v13, v64, 1.0
	v_fmac_f32_e32 v64, v65, v64
	v_div_scale_f32 v65, vcc, 1.0, v12, 1.0
	v_mul_f32_e32 v69, v65, v64
	v_fma_f32 v70, -v13, v69, v65
	v_rcp_f32_e32 v12, v12
	s_nop 0
	s_nop 0
	v_mul_f32_e32 v12, v12, v73
	v_mul_f32_e32 v9, v9, v12
	v_mul_f32_e32 v12, v63, v33
	v_fma_f32 v10, v12, v14, v10
	v_mul_f32_e32 v12, 0xbfb8aa3b, v10
	v_exp_f32_e32 v12, v12
	s_nop 0
	v_add_f32_e32 v12, 1.0, v12
	s_nop 0
	v_rcp_f32_e32 v12, v12
	s_nop 0
	s_nop 0
	v_mul_f32_e32 v10, v10, v12
	v_mul_f32_e32 v12, 0xbfb8aa3b, v74
	v_exp_f32_e32 v12, v12
	s_nop 0
	v_add_f32_e32 v12, 1.0, v12
	s_nop 0
	v_rcp_f32_e32 v12, v12
	s_nop 0
	s_nop 0
	v_mul_f32_e32 v12, v12, v74
	v_mul_f32_e32 v10, v10, v12
	v_mul_f32_e32 v12, v62, v33
	v_fmac_f32_e32 v11, v12, v15
	v_mul_f32_e32 v12, 0xbfb8aa3b, v11
	v_exp_f32_e32 v12, v12
	s_nop 0
	v_add_f32_e32 v12, 1.0, v12
	s_nop 0
	v_rcp_f32_e32 v12, v12
	s_nop 0
	s_nop 0
	v_mul_f32_e32 v11, v11, v12
	v_mul_f32_e32 v12, 0xbfb8aa3b, v68
	v_exp_f32_e32 v12, v12
	s_nop 0
	v_add_f32_e32 v12, 1.0, v12
	s_nop 0
	v_rcp_f32_e32 v12, v12
	s_nop 0
	s_nop 0
	v_mul_f32_e32 v12, v12, v68
	v_mul_f32_e32 v11, v11, v12
	v_mul_f32_e32 v12, v56, v33
	v_fma_f32 v0, v12, v4, v0
	v_mul_f32_e32 v4, 0xbfb8aa3b, v0
	v_exp_f32_e32 v4, v4
	s_nop 0
	v_add_f32_e32 v4, 1.0, v4
	s_nop 0
	v_rcp_f32_e32 v4, v4
	s_nop 0
	s_nop 0
	v_mul_f32_e32 v0, v0, v4
	v_mul_f32_e32 v4, 0xbfb8aa3b, v67
	v_exp_f32_e32 v4, v4
	s_nop 0
	v_add_f32_e32 v4, 1.0, v4
	s_nop 0
	v_rcp_f32_e32 v4, v4
	s_nop 0
	s_nop 0
	v_mul_f32_e32 v4, v4, v67
	v_mul_f32_e32 v4, v0, v4
	v_mul_f32_e32 v0, v57, v33
	v_fma_f32 v0, v0, v5, v1
	v_mul_f32_e32 v1, 0xbfb8aa3b, v0
	v_exp_f32_e32 v1, v1
	s_nop 0
	v_add_f32_e32 v1, 1.0, v1
	s_nop 0
	v_rcp_f32_e32 v1, v1
	s_nop 0
	s_nop 0
	v_mul_f32_e32 v0, v0, v1
	v_mul_f32_e32 v1, 0xbfb8aa3b, v66
	v_exp_f32_e32 v1, v1
	s_nop 0
	v_add_f32_e32 v1, 1.0, v1
	s_nop 0
	v_rcp_f32_e32 v1, v1
	s_nop 0
	s_nop 0
	v_mul_f32_e32 v1, v1, v66
	v_mul_f32_e32 v5, v0, v1
	v_mul_f32_e32 v0, v54, v33
	v_fma_f32 v0, v0, v6, v2
	v_mul_f32_e32 v1, 0xbfb8aa3b, v0
	v_exp_f32_e32 v1, v1
	s_nop 0
	v_add_f32_e32 v1, 1.0, v1
	s_nop 0
	v_rcp_f32_e32 v1, v1
	s_nop 0
	s_nop 0
	v_mul_f32_e32 v0, v0, v1
	v_mul_f32_e32 v1, 0xbfb8aa3b, v59
	v_exp_f32_e32 v1, v1
	s_nop 0
	v_add_f32_e32 v1, 1.0, v1
	s_nop 0
	v_rcp_f32_e32 v1, v1
	s_nop 0
	s_nop 0
	v_mul_f32_e32 v1, v1, v59
	v_mul_f32_e32 v6, v0, v1
	v_mul_f32_e32 v0, v55, v33
	v_fmac_f32_e32 v3, v0, v7
	v_mul_f32_e32 v0, 0xbfb8aa3b, v3
	v_exp_f32_e32 v0, v0
	s_nop 0
	v_add_f32_e32 v0, 1.0, v0
	s_nop 0
	v_rcp_f32_e32 v0, v0
	s_nop 0
	v_mul_f32_e32 v1, 0xbfb8aa3b, v58
	v_exp_f32_e32 v1, v1
	v_mul_f32_e32 v0, v3, v0
	v_add_f32_e32 v1, 1.0, v1
	s_nop 0
	v_rcp_f32_e32 v1, v1
	s_nop 0
	s_nop 0
	v_mul_f32_e32 v1, v1, v58
	v_mul_f32_e32 v3, v0, v1
	v_cvt_pk_bf16_f32 v0, v8, v9
	v_cvt_pk_bf16_f32 v1, v10, v11
	v_cvt_pk_bf16_f32 v2, v4, v5
	v_cvt_pk_bf16_f32 v3, v6, v3
	global_store_dwordx4 v[60:61], v[0:3], off offset:1024
	global_load_dwordx4 v[0:3], v82, s[58:59] offset:16
	s_nop 0
	global_load_dwordx4 v[4:7], v82, s[58:59]
	s_waitcnt vmcnt(0)
	v_add_f32_e32 v60, v52, v4
	v_add_f32_e32 v4, 0, v60
	v_add_f32_e32 v58, v53, v5
	v_add_f32_e32 v4, v4, v58
	v_add_f32_e32 v56, v50, v6
	v_add_f32_e32 v4, v4, v56
	v_add_f32_e32 v54, v51, v7
	v_add_f32_e32 v4, v4, v54
	v_add_f32_e32 v53, v48, v0
	v_add_f32_e32 v0, v4, v53
	v_add_f32_e32 v52, v49, v1
	v_add_f32_e32 v0, v0, v52
	v_add_f32_e32 v51, v46, v2
	v_add_f32_e32 v0, v0, v51
	v_add_f32_e32 v50, v47, v3
	v_add_f32_e32 v8, v0, v50
	global_load_dwordx4 v[0:3], v82, s[58:59] offset:2048
	global_load_dwordx4 v[4:7], v82, s[58:59] offset:2064
	s_waitcnt vmcnt(1)
	v_add_f32_e32 v49, v44, v0
	v_add_f32_e32 v0, v8, v49
	v_add_f32_e32 v48, v45, v1
	v_add_f32_e32 v0, v0, v48
	v_add_f32_e32 v47, v42, v2
	v_add_f32_e32 v0, v0, v47
	v_add_f32_e32 v46, v43, v3
	v_add_f32_e32 v8, v0, v46
	s_waitcnt vmcnt(0)
	v_pk_add_f32 v[2:3], v[40:41], v[4:5]
	v_pk_add_f32 v[0:1], v[38:39], v[6:7]
	v_add_f32_e32 v4, v8, v2
	v_add_f32_e32 v4, v4, v3
	v_add_f32_e32 v4, v4, v0
	v_add_f32_e32 v4, v4, v1
	ds_bpermute_b32 v5, v121, v4
	s_waitcnt lgkmcnt(0)
	v_add_f32_e32 v4, v4, v5
	ds_bpermute_b32 v5, v119, v4
	s_waitcnt lgkmcnt(0)
	v_add_f32_e32 v4, v4, v5
	ds_bpermute_b32 v5, v78, v4
	s_waitcnt lgkmcnt(0)
	v_add_f32_e32 v4, v4, v5
	ds_bpermute_b32 v5, v79, v4
	s_waitcnt lgkmcnt(0)
	v_add_f32_e32 v4, v4, v5
	ds_bpermute_b32 v5, v80, v4
	s_waitcnt lgkmcnt(0)
	v_add_f32_e32 v4, v4, v5
	ds_bpermute_b32 v5, v81, v4
	s_waitcnt lgkmcnt(0)
	v_add_f32_e32 v5, v4, v5
	v_fmac_f32_e32 v58, 0xba800000, v5
	v_fmac_f32_e32 v60, 0xba800000, v5
	v_mul_f32_e32 v6, v58, v58
	v_fmac_f32_e32 v6, v60, v60
	v_fmac_f32_e32 v56, 0xba800000, v5
	v_fmac_f32_e32 v6, v56, v56
	v_fmac_f32_e32 v54, 0xba800000, v5
	v_fmac_f32_e32 v6, v54, v54
	v_fmac_f32_e32 v53, 0xba800000, v5
	v_fmac_f32_e32 v6, v53, v53
	v_fmac_f32_e32 v52, 0xba800000, v5
	v_fmac_f32_e32 v6, v52, v52
	v_fmac_f32_e32 v51, 0xba800000, v5
	v_fmac_f32_e32 v6, v51, v51
	v_fmac_f32_e32 v50, 0xba800000, v5
	v_fmac_f32_e32 v6, v50, v50
	v_fmac_f32_e32 v49, 0xba800000, v5
	v_fmac_f32_e32 v6, v49, v49
	v_fmac_f32_e32 v48, 0xba800000, v5
	v_mul_f32_e32 v4, 0x3a800000, v5
	v_fmac_f32_e32 v6, v48, v48
	v_fmac_f32_e32 v47, 0xba800000, v5
	v_fmac_f32_e32 v6, v47, v47
	v_fmac_f32_e32 v46, 0xba800000, v5
	v_pk_add_f32 v[40:41], v[2:3], v[4:5] op_sel_hi:[1,0] neg_lo:[0,1] neg_hi:[0,1]
	v_fmac_f32_e32 v6, v46, v46
	v_pk_mul_f32 v[2:3], v[40:41], v[40:41]
	v_pk_add_f32 v[38:39], v[0:1], v[4:5] op_sel_hi:[1,0] neg_lo:[0,1] neg_hi:[0,1]
	v_add_f32_e32 v2, v2, v6
	v_add_f32_e32 v2, v3, v2
	v_pk_mul_f32 v[0:1], v[38:39], v[38:39]
	s_nop 0
	v_add_f32_e32 v0, v0, v2
	v_add_f32_e32 v1, v1, v0
	ds_bpermute_b32 v2, v121, v1
	v_or_b32_e32 v0, 2, v32
	s_waitcnt lgkmcnt(0)
	v_add_f32_e32 v1, v1, v2
	ds_bpermute_b32 v2, v119, v1
	s_waitcnt lgkmcnt(0)
	v_add_f32_e32 v1, v1, v2
	ds_bpermute_b32 v2, v78, v1
	s_waitcnt lgkmcnt(0)
	v_add_f32_e32 v1, v1, v2
	ds_bpermute_b32 v2, v79, v1
	s_waitcnt lgkmcnt(0)
	v_add_f32_e32 v1, v1, v2
	ds_bpermute_b32 v2, v80, v1
	s_waitcnt lgkmcnt(0)
	v_add_f32_e32 v1, v1, v2
	ds_bpermute_b32 v2, v81, v1
	s_waitcnt lgkmcnt(0)
	v_add_f32_e32 v1, v1, v2
	v_fmamk_f32 v1, v1, 0x3a800000, v211
	v_cmp_gt_f32_e32 vcc, s80, v1
	v_mul_f32_e32 v2, 0x4b800000, v1
	s_nop 0
	v_cndmask_b32_e32 v1, v1, v2, vcc
	v_rsq_f32_e32 v1, v1
	s_nop 0
	v_mul_f32_e32 v2, 0x45800000, v1
	v_cndmask_b32_e32 v33, v1, v2, vcc
	v_ashrrev_i32_e32 v1, 31, v0
	v_mad_i64_i32 v[2:3], s[4:5], v0, s82, v[34:35]
	v_lshlrev_b64 v[0:1], 11, v[0:1]
	v_lshl_add_u64 v[42:43], v[2:3], 0, s[6:7]
	v_lshl_add_u64 v[44:45], s[56:57], 0, v[0:1]
	global_load_dwordx4 v[4:7], v82, s[60:61] offset:16
	global_load_dwordx4 v[12:15], v82, s[60:61]
	global_load_dwordx4 v[0:3], v82, s[62:63] offset:16
	global_load_dwordx4 v[8:11], v82, s[62:63]
	v_lshl_add_u64 v[62:63], v[42:43], 0, v[168:169]
	global_load_dwordx4 v[62:65], v[62:63], off
	v_mul_f32_e32 v60, v60, v33
	v_lshl_add_u64 v[44:45], v[44:45], 0, v[168:169]
	v_lshl_add_u64 v[42:43], v[42:43], 0, v[36:37]
	v_mul_f32_e32 v49, v49, v33
	s_waitcnt vmcnt(1)
	v_fma_f32 v8, v12, v60, v8
	v_mul_f32_e32 v12, 0xbfb8aa3b, v8
	v_exp_f32_e32 v12, v12
	s_waitcnt vmcnt(0)
	v_lshlrev_b32_e32 v66, 16, v62
	v_and_b32_e32 v67, 0xffff0000, v62
	v_lshlrev_b32_e32 v68, 16, v63
	v_add_f32_e32 v12, 1.0, v12
	v_and_b32_e32 v62, 0xffff0000, v63
	v_lshlrev_b32_e32 v61, 16, v64
	v_and_b32_e32 v59, 0xffff0000, v64
	v_lshlrev_b32_e32 v57, 16, v65
	v_and_b32_e32 v55, 0xffff0000, v65
	v_rcp_f32_e32 v12, v12
	s_nop 0
	s_nop 0
	v_mul_f32_e32 v8, v8, v12
	v_mul_f32_e32 v12, 0xbfb8aa3b, v66
	v_exp_f32_e32 v12, v12
	s_nop 0
	v_add_f32_e32 v12, 1.0, v12
	v_div_scale_f32 v60, s[4:5], v12, v12, 1.0
	v_rcp_f32_e32 v63, v60
	s_nop 0
	v_fma_f32 v64, -v60, v63, 1.0
	v_fmac_f32_e32 v63, v64, v63
	v_div_scale_f32 v64, vcc, 1.0, v12, 1.0
	v_mul_f32_e32 v65, v64, v63
	v_fma_f32 v69, -v60, v65, v64
	v_fmac_f32_e32 v65, v69, v63
	v_rcp_f32_e32 v12, v12
	s_nop 0
	s_nop 0
	v_mul_f32_e32 v12, v12, v66
	v_mul_f32_e32 v8, v12, v8
	v_mul_f32_e32 v12, v58, v33
	v_fma_f32 v9, v13, v12, v9
	v_mul_f32_e32 v12, 0xbfb8aa3b, v9
	v_exp_f32_e32 v12, v12
	s_nop 0
	v_add_f32_e32 v12, 1.0, v12
	s_nop 0
	v_rcp_f32_e32 v12, v12
	s_nop 0
	s_nop 0
	v_mul_f32_e32 v9, v9, v12
	v_mul_f32_e32 v12, 0xbfb8aa3b, v67
	v_exp_f32_e32 v12, v12
	s_nop 0
	v_add_f32_e32 v12, 1.0, v12
	v_div_scale_f32 v13, s[4:5], v12, v12, 1.0
	v_rcp_f32_e32 v58, v13
	s_nop 0
	v_fma_f32 v60, -v13, v58, 1.0
	v_fmac_f32_e32 v58, v60, v58
	v_div_scale_f32 v60, vcc, 1.0, v12, 1.0
	v_mul_f32_e32 v63, v60, v58
	v_fma_f32 v64, -v13, v63, v60
	v_fmac_f32_e32 v63, v64, v58
	v_rcp_f32_e32 v12, v12
	s_nop 0
	s_nop 0
	v_mul_f32_e32 v12, v12, v67
	v_mul_f32_e32 v9, v12, v9
	v_mul_f32_e32 v12, v56, v33
	v_fma_f32 v10, v14, v12, v10
	v_mul_f32_e32 v12, 0xbfb8aa3b, v10
	v_exp_f32_e32 v12, v12
	s_nop 0
	v_add_f32_e32 v12, 1.0, v12
	s_nop 0
	v_rcp_f32_e32 v12, v12
	s_nop 0
	s_nop 0
	v_mul_f32_e32 v10, v10, v12
	v_mul_f32_e32 v12, 0xbfb8aa3b, v68
	v_exp_f32_e32 v12, v12
	s_nop 0
	v_add_f32_e32 v12, 1.0, v12
	v_div_scale_f32 v13, s[4:5], v12, v12, 1.0
	v_rcp_f32_e32 v14, v13
	s_nop 0
	v_fma_f32 v56, -v13, v14, 1.0
	v_fmac_f32_e32 v14, v56, v14
	v_div_scale_f32 v56, vcc, 1.0, v12, 1.0
	v_mul_f32_e32 v58, v56, v14
	v_fma_f32 v60, -v13, v58, v56
	v_rcp_f32_e32 v12, v12
	s_nop 0
	s_nop 0
	v_mul_f32_e32 v12, v12, v68
	v_mul_f32_e32 v10, v12, v10
	v_mul_f32_e32 v12, v54, v33
	v_fmac_f32_e32 v11, v15, v12
	v_mul_f32_e32 v12, 0xbfb8aa3b, v11
	v_exp_f32_e32 v12, v12
	s_nop 0
	v_add_f32_e32 v12, 1.0, v12
	s_nop 0
	v_rcp_f32_e32 v12, v12
	s_nop 0
	s_nop 0
	v_mul_f32_e32 v11, v11, v12
	v_mul_f32_e32 v12, 0xbfb8aa3b, v62
	v_exp_f32_e32 v12, v12
	s_nop 0
	v_add_f32_e32 v12, 1.0, v12
	s_nop 0
	v_rcp_f32_e32 v12, v12
	s_nop 0
	s_nop 0
	v_mul_f32_e32 v12, v12, v62
	v_mul_f32_e32 v11, v12, v11
	v_mul_f32_e32 v12, v53, v33
	v_fma_f32 v0, v4, v12, v0
	v_mul_f32_e32 v4, 0xbfb8aa3b, v0
	v_exp_f32_e32 v4, v4
	s_nop 0
	v_add_f32_e32 v4, 1.0, v4
	s_nop 0
	v_rcp_f32_e32 v4, v4
	s_nop 0
	s_nop 0
	v_mul_f32_e32 v0, v0, v4
	v_mul_f32_e32 v4, 0xbfb8aa3b, v61
	v_exp_f32_e32 v4, v4
	s_nop 0
	v_add_f32_e32 v4, 1.0, v4
	s_nop 0
	v_rcp_f32_e32 v4, v4
	s_nop 0
	s_nop 0
	v_mul_f32_e32 v4, v4, v61
	v_mul_f32_e32 v4, v4, v0
	v_mul_f32_e32 v0, v52, v33
	v_fma_f32 v0, v5, v0, v1
	v_mul_f32_e32 v1, 0xbfb8aa3b, v0
	v_exp_f32_e32 v1, v1
	s_nop 0
	v_add_f32_e32 v1, 1.0, v1
	s_nop 0
	v_rcp_f32_e32 v1, v1
	s_nop 0
	s_nop 0
	v_mul_f32_e32 v0, v0, v1
	v_mul_f32_e32 v1, 0xbfb8aa3b, v59
	v_exp_f32_e32 v1, v1
	s_nop 0
	v_add_f32_e32 v1, 1.0, v1
	s_nop 0
	v_rcp_f32_e32 v1, v1
	s_nop 0
	s_nop 0
	v_mul_f32_e32 v1, v1, v59
	v_mul_f32_e32 v5, v1, v0
	v_mul_f32_e32 v0, v51, v33
	v_fma_f32 v0, v6, v0, v2
	v_mul_f32_e32 v1, 0xbfb8aa3b, v0
	v_exp_f32_e32 v1, v1
	s_nop 0
	v_add_f32_e32 v1, 1.0, v1
	s_nop 0
	v_rcp_f32_e32 v1, v1
	s_nop 0
	s_nop 0
	v_mul_f32_e32 v0, v0, v1
	v_mul_f32_e32 v1, 0xbfb8aa3b, v57
	v_exp_f32_e32 v1, v1
	s_nop 0
	v_add_f32_e32 v1, 1.0, v1
	s_nop 0
	v_rcp_f32_e32 v1, v1
	s_nop 0
	s_nop 0
	v_mul_f32_e32 v1, v1, v57
	v_mul_f32_e32 v6, v1, v0
	v_mul_f32_e32 v0, v50, v33
	v_fmac_f32_e32 v3, v7, v0
	v_mul_f32_e32 v0, 0xbfb8aa3b, v3
	v_exp_f32_e32 v0, v0
	s_nop 0
	v_add_f32_e32 v0, 1.0, v0
	s_nop 0
	v_rcp_f32_e32 v0, v0
	s_nop 0
	v_mul_f32_e32 v1, 0xbfb8aa3b, v55
	v_exp_f32_e32 v1, v1
	v_mul_f32_e32 v0, v3, v0
	v_add_f32_e32 v1, 1.0, v1
	s_nop 0
	v_rcp_f32_e32 v1, v1
	s_nop 0
	s_nop 0
	v_mul_f32_e32 v1, v1, v55
	v_mul_f32_e32 v3, v1, v0
	v_cvt_pk_bf16_f32 v0, v8, v9
	v_cvt_pk_bf16_f32 v1, v10, v11
	v_cvt_pk_bf16_f32 v2, v4, v5
	v_cvt_pk_bf16_f32 v3, v6, v3
	global_store_dwordx4 v[44:45], v[0:3], off
	global_load_dwordx4 v[4:7], v82, s[60:61] offset:2064
	global_load_dwordx4 v[12:15], v82, s[60:61] offset:2048
	s_nop 0
	global_load_dwordx4 v[0:3], v82, s[62:63] offset:2064
	global_load_dwordx4 v[8:11], v82, s[62:63] offset:2048
	global_load_dwordx4 v[52:55], v[42:43], off
	s_waitcnt vmcnt(1)
	v_fma_f32 v8, v49, v12, v8
	v_mul_f32_e32 v12, 0xbfb8aa3b, v8
	v_exp_f32_e32 v12, v12
	s_waitcnt vmcnt(0)
	v_lshlrev_b32_e32 v56, 16, v52
	v_and_b32_e32 v57, 0xffff0000, v52
	v_lshlrev_b32_e32 v58, 16, v53
	v_add_f32_e32 v12, 1.0, v12
	v_and_b32_e32 v52, 0xffff0000, v53
	v_lshlrev_b32_e32 v51, 16, v54
	v_and_b32_e32 v50, 0xffff0000, v54
	v_lshlrev_b32_e32 v43, 16, v55
	v_and_b32_e32 v42, 0xffff0000, v55
	v_rcp_f32_e32 v12, v12
	s_nop 0
	s_nop 0
	v_mul_f32_e32 v8, v8, v12
	v_mul_f32_e32 v12, 0xbfb8aa3b, v56
	v_exp_f32_e32 v12, v12
	s_nop 0
	v_add_f32_e32 v12, 1.0, v12
	v_div_scale_f32 v49, s[4:5], v12, v12, 1.0
	v_rcp_f32_e32 v53, v49
	s_nop 0
	v_fma_f32 v54, -v49, v53, 1.0
	v_fmac_f32_e32 v53, v54, v53
	v_div_scale_f32 v54, vcc, 1.0, v12, 1.0
	v_mul_f32_e32 v55, v54, v53
	v_fma_f32 v59, -v49, v55, v54
	v_fmac_f32_e32 v55, v59, v53
	v_rcp_f32_e32 v12, v12
	s_nop 0
	s_nop 0
	v_mul_f32_e32 v12, v12, v56
	v_mul_f32_e32 v8, v8, v12
	v_mul_f32_e32 v12, v48, v33
	v_fma_f32 v9, v12, v13, v9
	v_mul_f32_e32 v12, 0xbfb8aa3b, v9
	v_exp_f32_e32 v12, v12
	s_nop 0
	v_add_f32_e32 v12, 1.0, v12
	s_nop 0
	v_rcp_f32_e32 v12, v12
	s_nop 0
	s_nop 0
	v_mul_f32_e32 v9, v9, v12
	v_mul_f32_e32 v12, 0xbfb8aa3b, v57
	v_exp_f32_e32 v12, v12
	s_nop 0
	v_add_f32_e32 v12, 1.0, v12
	v_div_scale_f32 v13, s[4:5], v12, v12, 1.0
	v_rcp_f32_e32 v48, v13
	s_nop 0
	v_fma_f32 v49, -v13, v48, 1.0
	v_fmac_f32_e32 v48, v49, v48
	v_div_scale_f32 v49, vcc, 1.0, v12, 1.0
	v_mul_f32_e32 v53, v49, v48
	v_fma_f32 v54, -v13, v53, v49
	v_fmac_f32_e32 v53, v54, v48
	v_rcp_f32_e32 v12, v12
	s_nop 0
	s_nop 0
	v_mul_f32_e32 v12, v12, v57
	v_mul_f32_e32 v9, v9, v12
	v_mul_f32_e32 v12, v47, v33
	v_fma_f32 v10, v12, v14, v10
	v_mul_f32_e32 v12, 0xbfb8aa3b, v10
	v_exp_f32_e32 v12, v12
	s_nop 0
	v_add_f32_e32 v12, 1.0, v12
	s_nop 0
	v_rcp_f32_e32 v12, v12
	s_nop 0
	s_nop 0
	v_mul_f32_e32 v10, v10, v12
	v_mul_f32_e32 v12, 0xbfb8aa3b, v58
	v_exp_f32_e32 v12, v12
	s_nop 0
	v_add_f32_e32 v12, 1.0, v12
	s_nop 0
	v_rcp_f32_e32 v12, v12
	s_nop 0
	s_nop 0
	v_mul_f32_e32 v12, v12, v58
	v_mul_f32_e32 v10, v10, v12
	v_mul_f32_e32 v12, v46, v33
	v_fmac_f32_e32 v11, v12, v15
	v_mul_f32_e32 v12, 0xbfb8aa3b, v11
	v_exp_f32_e32 v12, v12
	s_nop 0
	v_add_f32_e32 v12, 1.0, v12
	s_nop 0
	v_rcp_f32_e32 v12, v12
	s_nop 0
	s_nop 0
	v_mul_f32_e32 v11, v11, v12
	v_mul_f32_e32 v12, 0xbfb8aa3b, v52
	v_exp_f32_e32 v12, v12
	s_nop 0
	v_add_f32_e32 v12, 1.0, v12
	s_nop 0
	v_rcp_f32_e32 v12, v12
	s_nop 0
	s_nop 0
	v_mul_f32_e32 v12, v12, v52
	v_mul_f32_e32 v11, v11, v12
	v_mul_f32_e32 v12, v40, v33
	v_fma_f32 v0, v12, v4, v0
	v_mul_f32_e32 v4, 0xbfb8aa3b, v0
	v_exp_f32_e32 v4, v4
	s_nop 0
	v_add_f32_e32 v4, 1.0, v4
	s_nop 0
	v_rcp_f32_e32 v4, v4
	s_nop 0
	s_nop 0
	v_mul_f32_e32 v0, v0, v4
	v_mul_f32_e32 v4, 0xbfb8aa3b, v51
	v_exp_f32_e32 v4, v4
	s_nop 0
	v_add_f32_e32 v4, 1.0, v4
	s_nop 0
	v_rcp_f32_e32 v4, v4
	s_nop 0
	s_nop 0
	v_mul_f32_e32 v4, v4, v51
	v_mul_f32_e32 v4, v0, v4
	v_mul_f32_e32 v0, v41, v33
	v_fma_f32 v0, v0, v5, v1
	v_mul_f32_e32 v1, 0xbfb8aa3b, v0
	v_exp_f32_e32 v1, v1
	s_nop 0
	v_add_f32_e32 v1, 1.0, v1
	s_nop 0
	v_rcp_f32_e32 v1, v1
	s_nop 0
	s_nop 0
	v_mul_f32_e32 v0, v0, v1
	v_mul_f32_e32 v1, 0xbfb8aa3b, v50
	v_exp_f32_e32 v1, v1
	s_nop 0
	v_add_f32_e32 v1, 1.0, v1
	s_nop 0
	v_rcp_f32_e32 v1, v1
	s_nop 0
	s_nop 0
	v_mul_f32_e32 v1, v1, v50
	v_mul_f32_e32 v5, v0, v1
	v_mul_f32_e32 v0, v38, v33
	v_fma_f32 v0, v0, v6, v2
	v_mul_f32_e32 v1, 0xbfb8aa3b, v0
	v_exp_f32_e32 v1, v1
	s_nop 0
	v_add_f32_e32 v1, 1.0, v1
	s_nop 0
	v_rcp_f32_e32 v1, v1
	s_nop 0
	s_nop 0
	v_mul_f32_e32 v0, v0, v1
	v_mul_f32_e32 v1, 0xbfb8aa3b, v43
	v_exp_f32_e32 v1, v1
	s_nop 0
	v_add_f32_e32 v1, 1.0, v1
	s_nop 0
	v_rcp_f32_e32 v1, v1
	s_nop 0
	s_nop 0
	v_mul_f32_e32 v1, v1, v43
	v_mul_f32_e32 v6, v0, v1
	v_mul_f32_e32 v0, v39, v33
	v_fmac_f32_e32 v3, v0, v7
	v_mul_f32_e32 v0, 0xbfb8aa3b, v3
	v_exp_f32_e32 v0, v0
	s_nop 0
	v_add_f32_e32 v0, 1.0, v0
	s_nop 0
	v_rcp_f32_e32 v0, v0
	s_nop 0
	v_mul_f32_e32 v1, 0xbfb8aa3b, v42
	v_exp_f32_e32 v1, v1
	v_mul_f32_e32 v0, v3, v0
	v_add_f32_e32 v1, 1.0, v1
	s_nop 0
	v_rcp_f32_e32 v1, v1
	s_nop 0
	s_nop 0
	v_mul_f32_e32 v1, v1, v42
	v_mul_f32_e32 v3, v0, v1
	v_cvt_pk_bf16_f32 v0, v8, v9
	v_cvt_pk_bf16_f32 v1, v10, v11
	v_cvt_pk_bf16_f32 v2, v4, v5
	v_cvt_pk_bf16_f32 v3, v6, v3
	global_store_dwordx4 v[44:45], v[0:3], off offset:1024
	global_load_dwordx4 v[0:3], v82, s[58:59] offset:16
	s_nop 0
	global_load_dwordx4 v[4:7], v82, s[58:59]
	s_waitcnt vmcnt(1)
	v_add_f32_e32 v33, v26, v0
	s_waitcnt vmcnt(0)
	v_add_f32_e32 v41, v30, v4
	v_add_f32_e32 v4, 0, v41
	v_add_f32_e32 v40, v31, v5
	v_add_f32_e32 v4, v4, v40
	v_add_f32_e32 v39, v28, v6
	v_add_f32_e32 v4, v4, v39
	v_add_f32_e32 v38, v29, v7
	v_add_f32_e32 v4, v4, v38
	v_add_f32_e32 v0, v4, v33
	v_add_f32_e32 v31, v27, v1
	v_add_f32_e32 v0, v0, v31
	v_add_f32_e32 v30, v24, v2
	v_add_f32_e32 v0, v0, v30
	v_add_f32_e32 v29, v25, v3
	v_add_f32_e32 v8, v0, v29
	global_load_dwordx4 v[0:3], v82, s[58:59] offset:2048
	global_load_dwordx4 v[4:7], v82, s[58:59] offset:2064
	s_waitcnt vmcnt(1)
	v_add_f32_e32 v28, v22, v0
	v_add_f32_e32 v0, v8, v28
	v_add_f32_e32 v27, v23, v1
	v_add_f32_e32 v0, v0, v27
	v_add_f32_e32 v26, v20, v2
	v_add_f32_e32 v0, v0, v26
	v_add_f32_e32 v25, v21, v3
	v_add_f32_e32 v8, v0, v25
	s_waitcnt vmcnt(0)
	v_pk_add_f32 v[2:3], v[18:19], v[4:5]
	v_pk_add_f32 v[0:1], v[16:17], v[6:7]
	v_add_f32_e32 v4, v8, v2
	v_add_f32_e32 v4, v4, v3
	v_add_f32_e32 v4, v4, v0
	v_add_f32_e32 v4, v4, v1
	ds_bpermute_b32 v5, v121, v4
	s_waitcnt lgkmcnt(0)
	v_add_f32_e32 v4, v4, v5
	ds_bpermute_b32 v5, v119, v4
	s_waitcnt lgkmcnt(0)
	v_add_f32_e32 v4, v4, v5
	ds_bpermute_b32 v5, v78, v4
	s_waitcnt lgkmcnt(0)
	v_add_f32_e32 v4, v4, v5
	ds_bpermute_b32 v5, v79, v4
	s_waitcnt lgkmcnt(0)
	v_add_f32_e32 v4, v4, v5
	ds_bpermute_b32 v5, v80, v4
	s_waitcnt lgkmcnt(0)
	v_add_f32_e32 v4, v4, v5
	ds_bpermute_b32 v5, v81, v4
	s_waitcnt lgkmcnt(0)
	v_add_f32_e32 v5, v4, v5
	v_fmac_f32_e32 v40, 0xba800000, v5
	v_fmac_f32_e32 v41, 0xba800000, v5
	v_mul_f32_e32 v6, v40, v40
	v_fmac_f32_e32 v6, v41, v41
	v_fmac_f32_e32 v39, 0xba800000, v5
	v_fmac_f32_e32 v6, v39, v39
	v_fmac_f32_e32 v38, 0xba800000, v5
	v_fmac_f32_e32 v6, v38, v38
	v_fmac_f32_e32 v33, 0xba800000, v5
	v_fmac_f32_e32 v6, v33, v33
	v_fmac_f32_e32 v31, 0xba800000, v5
	v_fmac_f32_e32 v6, v31, v31
	v_fmac_f32_e32 v30, 0xba800000, v5
	v_fmac_f32_e32 v6, v30, v30
	v_fmac_f32_e32 v29, 0xba800000, v5
	v_fmac_f32_e32 v6, v29, v29
	v_fmac_f32_e32 v28, 0xba800000, v5
	v_fmac_f32_e32 v6, v28, v28
	v_fmac_f32_e32 v27, 0xba800000, v5
	v_mul_f32_e32 v4, 0x3a800000, v5
	v_fmac_f32_e32 v6, v27, v27
	v_fmac_f32_e32 v26, 0xba800000, v5
	v_fmac_f32_e32 v6, v26, v26
	v_fmac_f32_e32 v25, 0xba800000, v5
	v_pk_add_f32 v[18:19], v[2:3], v[4:5] op_sel_hi:[1,0] neg_lo:[0,1] neg_hi:[0,1]
	v_fmac_f32_e32 v6, v25, v25
	v_pk_mul_f32 v[2:3], v[18:19], v[18:19]
	v_pk_add_f32 v[16:17], v[0:1], v[4:5] op_sel_hi:[1,0] neg_lo:[0,1] neg_hi:[0,1]
	v_add_f32_e32 v2, v2, v6
	v_add_f32_e32 v2, v3, v2
	v_pk_mul_f32 v[0:1], v[16:17], v[16:17]
	s_nop 0
	v_add_f32_e32 v0, v0, v2
	v_add_f32_e32 v1, v1, v0
	ds_bpermute_b32 v2, v121, v1
	v_or_b32_e32 v0, 3, v32
	s_waitcnt lgkmcnt(0)
	v_add_f32_e32 v1, v1, v2
	ds_bpermute_b32 v2, v119, v1
	s_waitcnt lgkmcnt(0)
	v_add_f32_e32 v1, v1, v2
	ds_bpermute_b32 v2, v78, v1
	s_waitcnt lgkmcnt(0)
	v_add_f32_e32 v1, v1, v2
	ds_bpermute_b32 v2, v79, v1
	s_waitcnt lgkmcnt(0)
	v_add_f32_e32 v1, v1, v2
	ds_bpermute_b32 v2, v80, v1
	s_waitcnt lgkmcnt(0)
	v_add_f32_e32 v1, v1, v2
	ds_bpermute_b32 v2, v81, v1
	s_waitcnt lgkmcnt(0)
	v_add_f32_e32 v1, v1, v2
	v_fmamk_f32 v1, v1, 0x3a800000, v211
	v_cmp_gt_f32_e32 vcc, s80, v1
	v_mul_f32_e32 v2, 0x4b800000, v1
	s_nop 0
	v_cndmask_b32_e32 v1, v1, v2, vcc
	v_rsq_f32_e32 v1, v1
	s_nop 0
	v_mul_f32_e32 v2, 0x45800000, v1
	v_cndmask_b32_e32 v24, v1, v2, vcc
	v_ashrrev_i32_e32 v1, 31, v0
	v_mad_i64_i32 v[2:3], s[4:5], v0, s82, v[34:35]
	v_lshlrev_b64 v[0:1], 11, v[0:1]
	v_lshl_add_u64 v[20:21], v[2:3], 0, s[6:7]
	v_lshl_add_u64 v[22:23], s[56:57], 0, v[0:1]
	global_load_dwordx4 v[4:7], v82, s[60:61] offset:16
	global_load_dwordx4 v[12:15], v82, s[60:61]
	global_load_dwordx4 v[0:3], v82, s[62:63] offset:16
	global_load_dwordx4 v[8:11], v82, s[62:63]
	v_lshl_add_u64 v[34:35], v[20:21], 0, v[168:169]
	global_load_dwordx4 v[42:45], v[34:35], off
	v_mul_f32_e32 v41, v41, v24
	v_lshl_add_u64 v[22:23], v[22:23], 0, v[168:169]
	v_lshl_add_u64 v[20:21], v[20:21], 0, v[36:37]
	v_mul_f32_e32 v28, v28, v24
	s_waitcnt vmcnt(1)
	v_fma_f32 v8, v12, v41, v8
	v_mul_f32_e32 v12, 0xbfb8aa3b, v8
	v_exp_f32_e32 v12, v12
	s_waitcnt vmcnt(0)
	v_lshlrev_b32_e32 v46, 16, v42
	v_and_b32_e32 v47, 0xffff0000, v42
	v_lshlrev_b32_e32 v42, 16, v44
	v_add_f32_e32 v12, 1.0, v12
	v_and_b32_e32 v35, 0xffff0000, v44
	v_lshlrev_b32_e32 v34, 16, v45
	v_and_b32_e32 v32, 0xffff0000, v45
	v_lshlrev_b32_e32 v48, 16, v43
	v_rcp_f32_e32 v12, v12
	s_nop 0
	s_nop 0
	v_mul_f32_e32 v8, v8, v12
	v_mul_f32_e32 v12, 0xbfb8aa3b, v46
	v_exp_f32_e32 v12, v12
	v_and_b32_e32 v43, 0xffff0000, v43
	v_add_f32_e32 v12, 1.0, v12
	v_div_scale_f32 v41, s[4:5], v12, v12, 1.0
	v_rcp_f32_e32 v44, v41
	s_nop 0
	v_fma_f32 v45, -v41, v44, 1.0
	v_fmac_f32_e32 v44, v45, v44
	v_div_scale_f32 v45, vcc, 1.0, v12, 1.0
	v_mul_f32_e32 v49, v45, v44
	v_fma_f32 v50, -v41, v49, v45
	v_fmac_f32_e32 v49, v50, v44
	v_rcp_f32_e32 v12, v12
	s_nop 0
	s_nop 0
	v_mul_f32_e32 v12, v12, v46
	v_mul_f32_e32 v8, v12, v8
	v_mul_f32_e32 v12, v40, v24
	v_fma_f32 v9, v13, v12, v9
	v_mul_f32_e32 v12, 0xbfb8aa3b, v9
	v_exp_f32_e32 v12, v12
	s_nop 0
	v_add_f32_e32 v12, 1.0, v12
	s_nop 0
	v_rcp_f32_e32 v12, v12
	s_nop 0
	s_nop 0
	v_mul_f32_e32 v9, v9, v12
	v_mul_f32_e32 v12, 0xbfb8aa3b, v47
	v_exp_f32_e32 v12, v12
	s_nop 0
	v_add_f32_e32 v12, 1.0, v12
	v_div_scale_f32 v13, s[4:5], v12, v12, 1.0
	v_rcp_f32_e32 v40, v13
	s_nop 0
	v_fma_f32 v41, -v13, v40, 1.0
	v_fmac_f32_e32 v40, v41, v40
	v_div_scale_f32 v41, vcc, 1.0, v12, 1.0
	v_mul_f32_e32 v44, v41, v40
	v_fma_f32 v45, -v13, v44, v41
	v_fmac_f32_e32 v44, v45, v40
	v_rcp_f32_e32 v12, v12
	s_nop 0
	s_nop 0
	v_mul_f32_e32 v12, v12, v47
	v_mul_f32_e32 v9, v12, v9
	v_mul_f32_e32 v12, v39, v24
	v_fma_f32 v10, v14, v12, v10
	v_mul_f32_e32 v12, 0xbfb8aa3b, v10
	v_exp_f32_e32 v12, v12
	s_nop 0
	v_add_f32_e32 v12, 1.0, v12
	s_nop 0
	v_rcp_f32_e32 v12, v12
	s_nop 0
	s_nop 0
	v_mul_f32_e32 v10, v10, v12
	v_mul_f32_e32 v12, 0xbfb8aa3b, v48
	v_exp_f32_e32 v12, v12
	s_nop 0
	v_add_f32_e32 v12, 1.0, v12
	v_div_scale_f32 v13, s[4:5], v12, v12, 1.0
	v_rcp_f32_e32 v14, v13
	s_nop 0
	v_fma_f32 v39, -v13, v14, 1.0
	v_fmac_f32_e32 v14, v39, v14
	v_div_scale_f32 v39, vcc, 1.0, v12, 1.0
	v_mul_f32_e32 v40, v39, v14
	v_fma_f32 v41, -v13, v40, v39
	v_fmac_f32_e32 v40, v41, v14
	v_rcp_f32_e32 v12, v12
	s_nop 0
	s_nop 0
	v_mul_f32_e32 v12, v12, v48
	v_mul_f32_e32 v10, v12, v10
	v_mul_f32_e32 v12, v38, v24
	v_fmac_f32_e32 v11, v15, v12
	v_mul_f32_e32 v12, 0xbfb8aa3b, v11
	v_exp_f32_e32 v12, v12
	s_nop 0
	v_add_f32_e32 v12, 1.0, v12
	s_nop 0
	v_rcp_f32_e32 v12, v12
	s_nop 0
	s_nop 0
	v_mul_f32_e32 v11, v11, v12
	v_mul_f32_e32 v12, 0xbfb8aa3b, v43
	v_exp_f32_e32 v12, v12
	s_nop 0
	v_add_f32_e32 v12, 1.0, v12
	v_div_scale_f32 v13, s[4:5], v12, v12, 1.0
	v_rcp_f32_e32 v14, v13
	s_nop 0
	v_fma_f32 v15, -v13, v14, 1.0
	v_fmac_f32_e32 v14, v15, v14
	v_div_scale_f32 v15, vcc, 1.0, v12, 1.0
	v_mul_f32_e32 v38, v15, v14
	v_fma_f32 v39, -v13, v38, v15
	v_rcp_f32_e32 v12, v12
	s_nop 0
	s_nop 0
	v_mul_f32_e32 v12, v12, v43
	v_mul_f32_e32 v11, v12, v11
	v_mul_f32_e32 v12, v33, v24
	v_fma_f32 v0, v4, v12, v0
	v_mul_f32_e32 v4, 0xbfb8aa3b, v0
	v_exp_f32_e32 v4, v4
	s_nop 0
	v_add_f32_e32 v4, 1.0, v4
	s_nop 0
	v_rcp_f32_e32 v4, v4
	s_nop 0
	s_nop 0
	v_mul_f32_e32 v0, v0, v4
	v_mul_f32_e32 v4, 0xbfb8aa3b, v42
	v_exp_f32_e32 v4, v4
	s_nop 0
	v_add_f32_e32 v4, 1.0, v4
	s_nop 0
	v_rcp_f32_e32 v4, v4
	s_nop 0
	s_nop 0
	v_mul_f32_e32 v4, v4, v42
	v_mul_f32_e32 v4, v4, v0
	v_mul_f32_e32 v0, v31, v24
	v_fma_f32 v0, v5, v0, v1
	v_mul_f32_e32 v1, 0xbfb8aa3b, v0
	v_exp_f32_e32 v1, v1
	s_nop 0
	v_add_f32_e32 v1, 1.0, v1
	s_nop 0
	v_rcp_f32_e32 v1, v1
	s_nop 0
	s_nop 0
	v_mul_f32_e32 v0, v0, v1
	v_mul_f32_e32 v1, 0xbfb8aa3b, v35
	v_exp_f32_e32 v1, v1
	s_nop 0
	v_add_f32_e32 v1, 1.0, v1
	s_nop 0
	v_rcp_f32_e32 v1, v1
	s_nop 0
	s_nop 0
	v_mul_f32_e32 v1, v1, v35
	v_mul_f32_e32 v5, v1, v0
	v_mul_f32_e32 v0, v30, v24
	v_fma_f32 v0, v6, v0, v2
	v_mul_f32_e32 v1, 0xbfb8aa3b, v0
	v_exp_f32_e32 v1, v1
	s_nop 0
	v_add_f32_e32 v1, 1.0, v1
	s_nop 0
	v_rcp_f32_e32 v1, v1
	s_nop 0
	s_nop 0
	v_mul_f32_e32 v0, v0, v1
	v_mul_f32_e32 v1, 0xbfb8aa3b, v34
	v_exp_f32_e32 v1, v1
	s_nop 0
	v_add_f32_e32 v1, 1.0, v1
	s_nop 0
	v_rcp_f32_e32 v1, v1
	s_nop 0
	s_nop 0
	v_mul_f32_e32 v1, v1, v34
	v_mul_f32_e32 v6, v1, v0
	v_mul_f32_e32 v0, v29, v24
	v_fmac_f32_e32 v3, v7, v0
	v_mul_f32_e32 v0, 0xbfb8aa3b, v3
	v_exp_f32_e32 v0, v0
	s_nop 0
	v_add_f32_e32 v0, 1.0, v0
	s_nop 0
	v_rcp_f32_e32 v0, v0
	s_nop 0
	v_mul_f32_e32 v1, 0xbfb8aa3b, v32
	v_exp_f32_e32 v1, v1
	v_mul_f32_e32 v0, v3, v0
	v_add_f32_e32 v1, 1.0, v1
	s_nop 0
	v_rcp_f32_e32 v1, v1
	s_nop 0
	s_nop 0
	v_mul_f32_e32 v1, v1, v32
	v_mul_f32_e32 v3, v1, v0
	v_cvt_pk_bf16_f32 v0, v8, v9
	v_cvt_pk_bf16_f32 v1, v10, v11
	v_cvt_pk_bf16_f32 v2, v4, v5
	v_cvt_pk_bf16_f32 v3, v6, v3
	global_store_dwordx4 v[22:23], v[0:3], off
	global_load_dwordx4 v[4:7], v82, s[60:61] offset:2064
	global_load_dwordx4 v[12:15], v82, s[60:61] offset:2048
	s_nop 0
	global_load_dwordx4 v[0:3], v82, s[62:63] offset:2064
	global_load_dwordx4 v[8:11], v82, s[62:63] offset:2048
	global_load_dwordx4 v[30:33], v[20:21], off
	s_waitcnt vmcnt(1)
	v_fma_f32 v8, v28, v12, v8
	v_mul_f32_e32 v12, 0xbfb8aa3b, v8
	v_exp_f32_e32 v12, v12
	s_waitcnt vmcnt(0)
	v_lshlrev_b32_e32 v34, 16, v30
	v_and_b32_e32 v35, 0xffff0000, v30
	v_lshlrev_b32_e32 v30, 16, v32
	v_add_f32_e32 v12, 1.0, v12
	v_and_b32_e32 v29, 0xffff0000, v32
	v_lshlrev_b32_e32 v21, 16, v33
	v_and_b32_e32 v20, 0xffff0000, v33
	v_lshlrev_b32_e32 v36, 16, v31
	v_rcp_f32_e32 v12, v12
	s_nop 0
	s_nop 0
	v_mul_f32_e32 v8, v8, v12
	v_mul_f32_e32 v12, 0xbfb8aa3b, v34
	v_exp_f32_e32 v12, v12
	v_and_b32_e32 v31, 0xffff0000, v31
	v_add_f32_e32 v12, 1.0, v12
	v_div_scale_f32 v28, s[4:5], v12, v12, 1.0
	v_rcp_f32_e32 v32, v28
	s_nop 0
	v_fma_f32 v33, -v28, v32, 1.0
	v_fmac_f32_e32 v32, v33, v32
	v_div_scale_f32 v33, vcc, 1.0, v12, 1.0
	v_mul_f32_e32 v37, v33, v32
	v_fma_f32 v38, -v28, v37, v33
	v_fmac_f32_e32 v37, v38, v32
	v_rcp_f32_e32 v12, v12
	s_nop 0
	s_nop 0
	v_mul_f32_e32 v12, v12, v34
	v_mul_f32_e32 v8, v8, v12
	v_mul_f32_e32 v12, v27, v24
	v_fma_f32 v9, v12, v13, v9
	v_mul_f32_e32 v12, 0xbfb8aa3b, v9
	v_exp_f32_e32 v12, v12
	s_nop 0
	v_add_f32_e32 v12, 1.0, v12
	s_nop 0
	v_rcp_f32_e32 v12, v12
	s_nop 0
	s_nop 0
	v_mul_f32_e32 v9, v9, v12
	v_mul_f32_e32 v12, 0xbfb8aa3b, v35
	v_exp_f32_e32 v12, v12
	s_nop 0
	v_add_f32_e32 v12, 1.0, v12
	v_div_scale_f32 v13, s[4:5], v12, v12, 1.0
	v_rcp_f32_e32 v27, v13
	s_nop 0
	v_fma_f32 v28, -v13, v27, 1.0
	v_fmac_f32_e32 v27, v28, v27
	v_div_scale_f32 v28, vcc, 1.0, v12, 1.0
	v_mul_f32_e32 v32, v28, v27
	v_fma_f32 v33, -v13, v32, v28
	v_fmac_f32_e32 v32, v33, v27
	v_rcp_f32_e32 v12, v12
	s_nop 0
	s_nop 0
	v_mul_f32_e32 v12, v12, v35
	v_mul_f32_e32 v9, v9, v12
	v_mul_f32_e32 v12, v26, v24
	v_fma_f32 v10, v12, v14, v10
	v_mul_f32_e32 v12, 0xbfb8aa3b, v10
	v_exp_f32_e32 v12, v12
	s_nop 0
	v_add_f32_e32 v12, 1.0, v12
	s_nop 0
	v_rcp_f32_e32 v12, v12
	s_nop 0
	s_nop 0
	v_mul_f32_e32 v10, v10, v12
	v_mul_f32_e32 v12, 0xbfb8aa3b, v36
	v_exp_f32_e32 v12, v12
	s_nop 0
	v_add_f32_e32 v12, 1.0, v12
	v_div_scale_f32 v13, s[4:5], v12, v12, 1.0
	v_rcp_f32_e32 v14, v13
	s_nop 0
	v_fma_f32 v26, -v13, v14, 1.0
	v_fmac_f32_e32 v14, v26, v14
	v_div_scale_f32 v26, vcc, 1.0, v12, 1.0
	v_mul_f32_e32 v27, v26, v14
	v_fma_f32 v28, -v13, v27, v26
	v_fmac_f32_e32 v27, v28, v14
	v_rcp_f32_e32 v12, v12
	s_nop 0
	s_nop 0
	v_mul_f32_e32 v12, v12, v36
	v_mul_f32_e32 v10, v10, v12
	v_mul_f32_e32 v12, v25, v24
	v_fmac_f32_e32 v11, v12, v15
	v_mul_f32_e32 v12, 0xbfb8aa3b, v11
	v_exp_f32_e32 v12, v12
	s_nop 0
	v_add_f32_e32 v12, 1.0, v12
	s_nop 0
	v_rcp_f32_e32 v12, v12
	s_nop 0
	s_nop 0
	v_mul_f32_e32 v11, v11, v12
	v_mul_f32_e32 v12, 0xbfb8aa3b, v31
	v_exp_f32_e32 v12, v12
	s_nop 0
	v_add_f32_e32 v12, 1.0, v12
	v_div_scale_f32 v13, s[4:5], v12, v12, 1.0
	v_rcp_f32_e32 v14, v13
	s_nop 0
	v_fma_f32 v15, -v13, v14, 1.0
	v_fmac_f32_e32 v14, v15, v14
	v_div_scale_f32 v15, vcc, 1.0, v12, 1.0
	v_mul_f32_e32 v25, v15, v14
	v_fma_f32 v26, -v13, v25, v15
	v_fmac_f32_e32 v25, v26, v14
	v_rcp_f32_e32 v12, v12
	s_nop 0
	s_nop 0
	v_mul_f32_e32 v12, v12, v31
	v_mul_f32_e32 v11, v11, v12
	v_mul_f32_e32 v12, v18, v24
	v_fma_f32 v0, v12, v4, v0
	v_mul_f32_e32 v4, 0xbfb8aa3b, v0
	v_exp_f32_e32 v4, v4
	s_nop 0
	v_add_f32_e32 v4, 1.0, v4
	s_nop 0
	v_rcp_f32_e32 v4, v4
	s_nop 0
	s_nop 0
	v_mul_f32_e32 v0, v0, v4
	v_mul_f32_e32 v4, 0xbfb8aa3b, v30
	v_exp_f32_e32 v4, v4
	s_nop 0
	v_add_f32_e32 v4, 1.0, v4
	v_div_scale_f32 v12, s[4:5], v4, v4, 1.0
	v_rcp_f32_e32 v13, v12
	s_nop 0
	v_fma_f32 v14, -v12, v13, 1.0
	v_fmac_f32_e32 v13, v14, v13
	v_div_scale_f32 v14, vcc, 1.0, v4, 1.0
	v_mul_f32_e32 v15, v14, v13
	v_fma_f32 v18, -v12, v15, v14
	v_rcp_f32_e32 v4, v4
	s_nop 0
	s_nop 0
	v_mul_f32_e32 v4, v4, v30
	v_mul_f32_e32 v4, v0, v4
	v_mul_f32_e32 v0, v19, v24
	v_fma_f32 v0, v0, v5, v1
	v_mul_f32_e32 v1, 0xbfb8aa3b, v0
	v_exp_f32_e32 v1, v1
	s_nop 0
	v_add_f32_e32 v1, 1.0, v1
	s_nop 0
	v_rcp_f32_e32 v1, v1
	s_nop 0
	s_nop 0
	v_mul_f32_e32 v0, v0, v1
	v_mul_f32_e32 v1, 0xbfb8aa3b, v29
	v_exp_f32_e32 v1, v1
	s_nop 0
	v_add_f32_e32 v1, 1.0, v1
	v_div_scale_f32 v5, s[4:5], v1, v1, 1.0
	v_rcp_f32_e32 v12, v5
	s_nop 0
	v_fma_f32 v13, -v5, v12, 1.0
	v_fmac_f32_e32 v12, v13, v12
	v_div_scale_f32 v13, vcc, 1.0, v1, 1.0
	v_mul_f32_e32 v14, v13, v12
	v_fma_f32 v15, -v5, v14, v13
	v_rcp_f32_e32 v1, v1
	s_nop 0
	s_nop 0
	v_mul_f32_e32 v1, v1, v29
	v_mul_f32_e32 v5, v0, v1
	v_mul_f32_e32 v0, v16, v24
	v_fma_f32 v0, v0, v6, v2
	v_mul_f32_e32 v1, 0xbfb8aa3b, v0
	v_exp_f32_e32 v1, v1
	s_nop 0
	v_add_f32_e32 v1, 1.0, v1
	s_nop 0
	v_rcp_f32_e32 v1, v1
	s_nop 0
	s_nop 0
	v_mul_f32_e32 v0, v0, v1
	v_mul_f32_e32 v1, 0xbfb8aa3b, v21
	v_exp_f32_e32 v1, v1
	s_nop 0
	v_add_f32_e32 v1, 1.0, v1
	v_div_scale_f32 v2, s[4:5], v1, v1, 1.0
	v_rcp_f32_e32 v6, v2
	s_nop 0
	v_fma_f32 v12, -v2, v6, 1.0
	v_fmac_f32_e32 v6, v12, v6
	v_div_scale_f32 v12, vcc, 1.0, v1, 1.0
	v_mul_f32_e32 v13, v12, v6
	v_fma_f32 v14, -v2, v13, v12
	v_rcp_f32_e32 v1, v1
	s_nop 0
	s_nop 0
	v_mul_f32_e32 v1, v1, v21
	v_mul_f32_e32 v6, v0, v1
	v_mul_f32_e32 v0, v17, v24
	v_fmac_f32_e32 v3, v0, v7
	v_mul_f32_e32 v0, 0xbfb8aa3b, v3
	v_exp_f32_e32 v0, v0
	s_nop 0
	v_add_f32_e32 v0, 1.0, v0
	s_nop 0
	v_rcp_f32_e32 v0, v0
	s_nop 0
	v_mul_f32_e32 v1, 0xbfb8aa3b, v20
	v_exp_f32_e32 v1, v1
	v_mul_f32_e32 v0, v3, v0
	v_add_f32_e32 v1, 1.0, v1
	v_div_scale_f32 v2, s[4:5], v1, v1, 1.0
	v_rcp_f32_e32 v3, v2
	s_load_dwordx4 s[4:7], s[96:97], 0x118
	v_fma_f32 v7, -v2, v3, 1.0
	v_fmac_f32_e32 v3, v7, v3
	v_div_scale_f32 v7, vcc, 1.0, v1, 1.0
	v_mul_f32_e32 v12, v7, v3
	v_fma_f32 v13, -v2, v12, v7
	v_fmac_f32_e32 v12, v13, v3
	v_rcp_f32_e32 v1, v1
	s_nop 0
	s_nop 0
	v_mul_f32_e32 v1, v1, v20
	s_waitcnt lgkmcnt(0)
	s_add_i32 s52, s52, s6
	v_mul_f32_e32 v3, v0, v1
	s_cmpk_gt_i32 s52, 0x1ff
	v_cvt_pk_bf16_f32 v0, v8, v9
	v_cvt_pk_bf16_f32 v1, v10, v11
	v_cvt_pk_bf16_f32 v2, v4, v5
	v_cvt_pk_bf16_f32 v3, v6, v3
	global_store_dwordx4 v[22:23], v[0:3], off offset:1024
	s_cbranch_scc0 .LBB0_343
